# FoX items: hand-written streaming loop, lean log2-domain softmax, K/V/augmented chunk prefetched two tile-steps ahead, registers saved/restored via LDS
# baseline (speedup 1.0000x reference)
.Lfox_entry:
	s_waitcnt vmcnt(0)
	v_lshlrev_b32_e32 v2, 2, v220
	v_add_u32_e32 v3, 0x10000, v2
	ds_write_b32 v2, v162 offset:0
	ds_write_b32 v2, v163 offset:2048
	ds_write_b32 v2, v164 offset:4096
	ds_write_b32 v2, v165 offset:6144
	ds_write_b32 v2, v166 offset:8192
	ds_write_b32 v2, v167 offset:10240
	ds_write_b32 v2, v168 offset:12288
	ds_write_b32 v2, v169 offset:14336
	ds_write_b32 v2, v170 offset:16384
	ds_write_b32 v2, v183 offset:18432
	ds_write_b32 v2, v184 offset:20480
	ds_write_b32 v2, v185 offset:22528
	ds_write_b32 v2, v186 offset:24576
	ds_write_b32 v2, v187 offset:26624
	ds_write_b32 v2, v188 offset:28672
	ds_write_b32 v2, v189 offset:30720
	ds_write_b32 v2, v190 offset:32768
	ds_write_b32 v2, v191 offset:34816
	ds_write_b32 v2, v192 offset:36864
	ds_write_b32 v2, v193 offset:38912
	ds_write_b32 v2, v194 offset:40960
	ds_write_b32 v2, v195 offset:43008
	ds_write_b32 v2, v196 offset:45056
	ds_write_b32 v2, v197 offset:47104
	ds_write_b32 v2, v198 offset:49152
	ds_write_b32 v2, v199 offset:51200
	ds_write_b32 v2, v200 offset:53248
	ds_write_b32 v2, v201 offset:55296
	ds_write_b32 v2, v202 offset:57344
	ds_write_b32 v2, v203 offset:59392
	ds_write_b32 v2, v204 offset:61440
	ds_write_b32 v2, v205 offset:63488
	ds_write_b32 v3, v206 offset:0
	ds_write_b32 v3, v207 offset:2048
	ds_write_b32 v3, v208 offset:4096
	ds_write_b32 v3, v209 offset:6144
	ds_write_b32 v3, v210 offset:8192
	ds_write_b32 v3, v211 offset:10240
	ds_write_b32 v3, v212 offset:12288
	ds_write_b32 v3, v213 offset:14336
	ds_write_b32 v3, v214 offset:16384
	ds_write_b32 v3, v215 offset:18432
	ds_write_b32 v3, v216 offset:20480
	ds_write_b32 v3, v146 offset:22528
	ds_write_b32 v3, v147 offset:24576
	ds_write_b32 v3, v148 offset:26624
	ds_write_b32 v3, v149 offset:28672
	ds_write_b32 v3, v150 offset:30720
	ds_write_b32 v3, v151 offset:32768
	ds_write_b32 v3, v152 offset:34816
	ds_write_b32 v3, v153 offset:36864
	ds_write_b32 v3, v154 offset:38912
	ds_write_b32 v3, v155 offset:40960
	ds_write_b32 v3, v156 offset:43008
	ds_write_b32 v3, v157 offset:45056
	ds_write_b32 v3, v158 offset:47104
	ds_write_b32 v3, v159 offset:49152
	ds_write_b32 v3, v160 offset:51200
	ds_write_b32 v3, v161 offset:53248
	v_lshrrev_b32_e32 v2, 6, v220
	v_lshlrev_b32_e32 v2, 8, v2
	v_add_u32_e32 v2, 0x1d800, v2
	v_mov_b32_e32 v3, s2
	ds_write_b32 v2, v3 offset:0
	v_mov_b32_e32 v3, s3
	ds_write_b32 v2, v3 offset:4
	v_mov_b32_e32 v3, s4
	ds_write_b32 v2, v3 offset:8
	v_mov_b32_e32 v3, s5
	ds_write_b32 v2, v3 offset:12
	v_mov_b32_e32 v3, s6
	ds_write_b32 v2, v3 offset:16
	v_mov_b32_e32 v3, s7
	ds_write_b32 v2, v3 offset:20
	v_mov_b32_e32 v3, s8
	ds_write_b32 v2, v3 offset:24
	v_mov_b32_e32 v3, s9
	ds_write_b32 v2, v3 offset:28
	v_mov_b32_e32 v3, s10
	ds_write_b32 v2, v3 offset:32
	v_mov_b32_e32 v3, s11
	ds_write_b32 v2, v3 offset:36
	v_mov_b32_e32 v3, s12
	ds_write_b32 v2, v3 offset:40
	v_mov_b32_e32 v3, s13
	ds_write_b32 v2, v3 offset:44
	v_mov_b32_e32 v3, s14
	ds_write_b32 v2, v3 offset:48
	v_mov_b32_e32 v3, s15
	ds_write_b32 v2, v3 offset:52
	v_mov_b32_e32 v3, s16
	ds_write_b32 v2, v3 offset:56
	v_mov_b32_e32 v3, s17
	ds_write_b32 v2, v3 offset:60
	v_mov_b32_e32 v3, s18
	ds_write_b32 v2, v3 offset:64
	v_mov_b32_e32 v3, s19
	ds_write_b32 v2, v3 offset:68
	v_mov_b32_e32 v3, s20
	ds_write_b32 v2, v3 offset:72
	v_mov_b32_e32 v3, s21
	ds_write_b32 v2, v3 offset:76
	v_mov_b32_e32 v3, s22
	ds_write_b32 v2, v3 offset:80
	v_mov_b32_e32 v3, s23
	ds_write_b32 v2, v3 offset:84
	v_mov_b32_e32 v3, s24
	ds_write_b32 v2, v3 offset:88
	v_mov_b32_e32 v3, s25
	ds_write_b32 v2, v3 offset:92
	v_mov_b32_e32 v3, s26
	ds_write_b32 v2, v3 offset:96
	v_mov_b32_e32 v3, s27
	ds_write_b32 v2, v3 offset:100
	v_mov_b32_e32 v3, s28
	ds_write_b32 v2, v3 offset:104
	v_mov_b32_e32 v3, s29
	ds_write_b32 v2, v3 offset:108
	v_mov_b32_e32 v3, s30
	ds_write_b32 v2, v3 offset:112
	v_mov_b32_e32 v3, s31
	ds_write_b32 v2, v3 offset:116
	v_mov_b32_e32 v3, s34
	ds_write_b32 v2, v3 offset:120
	v_mov_b32_e32 v3, s35
	ds_write_b32 v2, v3 offset:124
	v_mov_b32_e32 v3, s36
	ds_write_b32 v2, v3 offset:128
	v_mov_b32_e32 v3, s37
	ds_write_b32 v2, v3 offset:132
	v_mov_b32_e32 v3, s38
	ds_write_b32 v2, v3 offset:136
	v_mov_b32_e32 v3, s39
	ds_write_b32 v2, v3 offset:140
	v_mov_b32_e32 v3, s40
	ds_write_b32 v2, v3 offset:144
	v_mov_b32_e32 v3, s41
	ds_write_b32 v2, v3 offset:148
	v_mov_b32_e32 v3, s42
	ds_write_b32 v2, v3 offset:152
	v_mov_b32_e32 v3, s43
	ds_write_b32 v2, v3 offset:156
	v_mov_b32_e32 v3, s44
	ds_write_b32 v2, v3 offset:160
	v_mov_b32_e32 v3, s45
	ds_write_b32 v2, v3 offset:164
	s_load_dwordx2 s[20:21], s[70:71], 0x98
	v_readlane_b32 s22, v254, 0
	v_and_b32_e32 v163, 31, v173
	v_lshrrev_b32_e32 v164, 5, v173
	v_lshlrev_b32_e32 v162, 4, v173
	v_lshlrev_b32_e32 v190, 4, v163
	v_mov_b32_e32 v193, 0xff800000
	v_lshlrev_b32_e32 v183, 2, v164
	v_sub_u32_e32 v170, v163, v183
	v_xor_b32_e32 v192, 32, v173
	v_lshlrev_b32_e32 v192, 2, v192
	s_mov_b32 s14, 0x3e38aa3b
	s_mov_b32 s44, -1
	s_mov_b32 s45, 0
	v_cmp_eq_u32_e32 vcc, 0, v164
	v_mov_b32_e32 v183, 0x3f803f80
	v_mov_b32_e32 v184, 0x3f80
	s_nop 0
	v_cndmask_b32_e32 v110, 0, v183, vcc
	v_cndmask_b32_e32 v111, 0, v184, vcc
	v_mov_b32_e32 v112, 0
	v_mov_b32_e32 v113, 0
	v_mov_b32_e32 v18, 0
	v_mov_b32_e32 v19, 0
	v_mov_b32_e32 v20, 0
	v_mov_b32_e32 v21, 0
	v_mov_b32_e32 v38, 0
	v_mov_b32_e32 v39, 0
	v_mov_b32_e32 v40, 0
	v_mov_b32_e32 v41, 0
	v_mov_b32_e32 v58, 0
	v_mov_b32_e32 v59, 0
	v_mov_b32_e32 v60, 0
	v_mov_b32_e32 v61, 0
	s_waitcnt lgkmcnt(0)
.Lfox_outer:
	s_lshr_b32 s23, s22, 6
	s_and_b32 s24, s22, 63
	s_lshr_b32 s25, s23, 2
	s_and_b32 s26, s23, 3
	s_lshl_b32 s17, s23, 19
	s_add_u32 s4, s20, s17
	s_addc_u32 s5, s21, 0
	s_add_u32 s6, s4, 0x1c600000
	s_addc_u32 s7, s5, 0
	s_add_u32 s4, s4, 0x1b600000
	s_addc_u32 s5, s5, 0
	s_lshl_b32 s17, s23, 16
	s_add_u32 s8, s20, s17
	s_addc_u32 s9, s21, 0
	s_add_u32 s8, s8, 0x2880000
	s_addc_u32 s9, s9, 0
	s_lshl_b32 s17, s23, 14
	s_add_u32 s10, s20, s17
	s_addc_u32 s11, s21, 0
	s_add_u32 s10, s10, 0x1da00000
	s_addc_u32 s11, s11, 0
	s_lshl_b32 s17, s25, 23
	s_lshl_b32 s18, s26, 7
	s_add_i32 s17, s17, s18
	s_add_u32 s12, s20, s17
	s_addc_u32 s13, s21, 0
	s_add_u32 s12, s12, 0x14600000
	s_addc_u32 s13, s13, 0
	s_add_u32 s2, s20, 0x5600000
	s_addc_u32 s3, s21, 0
	s_lshl_b32 s27, s25, 12
	s_sub_i32 s15, 0x7f, s24
	s_mov_b32 s28, 0
.Lfox_item:
	v_lshl_add_u32 v183, s15, 5, v163
	v_lshlrev_b32_e32 v191, 11, v183
	v_lshl_add_u32 v191, v164, 3, v191
	v_lshlrev_b32_e32 v184, 2, v183
	global_load_dword v167, v184, s[10:11]
	v_add_u32_e32 v183, s27, v183
	v_mul_u32_u24_e32 v183, 0x1600, v183
	v_lshl_add_u32 v183, v164, 4, v183
	s_lshl_b32 s17, s26, 7
	v_add_u32_e32 v183, s17, v183
	global_load_dwordx4 v[94:97], v183, s[2:3]
	global_load_dwordx4 v[98:101], v183, s[2:3] offset:32
	global_load_dwordx4 v[102:105], v183, s[2:3] offset:64
	global_load_dwordx4 v[106:109], v183, s[2:3] offset:96
	v_mov_b32_e32 v165, 0xf149f2ca
	v_mov_b32_e32 v166, 0
	v_mov_b32_e32 v114, 0
	v_mov_b32_e32 v115, 0
	v_mov_b32_e32 v116, 0
	v_mov_b32_e32 v117, 0
	v_mov_b32_e32 v118, 0
	v_mov_b32_e32 v119, 0
	v_mov_b32_e32 v120, 0
	v_mov_b32_e32 v121, 0
	v_mov_b32_e32 v122, 0
	v_mov_b32_e32 v123, 0
	v_mov_b32_e32 v124, 0
	v_mov_b32_e32 v125, 0
	v_mov_b32_e32 v126, 0
	v_mov_b32_e32 v127, 0
	v_mov_b32_e32 v128, 0
	v_mov_b32_e32 v129, 0
	v_mov_b32_e32 v130, 0
	v_mov_b32_e32 v131, 0
	v_mov_b32_e32 v132, 0
	v_mov_b32_e32 v133, 0
	v_mov_b32_e32 v134, 0
	v_mov_b32_e32 v135, 0
	v_mov_b32_e32 v136, 0
	v_mov_b32_e32 v137, 0
	v_mov_b32_e32 v138, 0
	v_mov_b32_e32 v139, 0
	v_mov_b32_e32 v140, 0
	v_mov_b32_e32 v141, 0
	v_mov_b32_e32 v142, 0
	v_mov_b32_e32 v143, 0
	v_mov_b32_e32 v144, 0
	v_mov_b32_e32 v145, 0
	s_mov_b32 s16, 0
	s_min_u32 s19, 1, s15
	s_lshl_b32 s17, s16, 12
	v_add_u32_e32 v183, s17, v162
	global_load_dwordx4 v[78:81], v183, s[6:7]
	global_load_dwordx4 v[82:85], v183, s[6:7] offset:1024
	global_load_dwordx4 v[86:89], v183, s[6:7] offset:2048
	global_load_dwordx4 v[90:93], v183, s[6:7] offset:3072
	s_lshl_b32 s17, s16, 12
	v_add_u32_e32 v183, s17, v162
	global_load_dwordx4 v[2:5], v183, s[4:5]
	global_load_dwordx4 v[6:9], v183, s[4:5] offset:1024
	global_load_dwordx4 v[10:13], v183, s[4:5] offset:2048
	global_load_dwordx4 v[14:17], v183, s[4:5] offset:3072
	s_lshl_b32 s17, s16, 9
	v_add_u32_e32 v183, s17, v190
	s_mov_b64 exec, s[44:45]
	global_load_dwordx4 v[18:21], v183, s[8:9]
	s_mov_b64 exec, -1
	s_lshl_b32 s17, s16, 12
	v_add_u32_e32 v183, s17, v162
	global_load_dwordx4 v[62:65], v183, s[6:7]
	global_load_dwordx4 v[66:69], v183, s[6:7] offset:1024
	global_load_dwordx4 v[70:73], v183, s[6:7] offset:2048
	global_load_dwordx4 v[74:77], v183, s[6:7] offset:3072
	s_lshl_b32 s17, s19, 12
	v_add_u32_e32 v183, s17, v162
	global_load_dwordx4 v[22:25], v183, s[4:5]
	global_load_dwordx4 v[26:29], v183, s[4:5] offset:1024
	global_load_dwordx4 v[30:33], v183, s[4:5] offset:2048
	global_load_dwordx4 v[34:37], v183, s[4:5] offset:3072
	s_lshl_b32 s17, s19, 9
	v_add_u32_e32 v183, s17, v190
	s_mov_b64 exec, s[44:45]
	global_load_dwordx4 v[38:41], v183, s[8:9]
	s_mov_b64 exec, -1
	s_waitcnt vmcnt(18)
	v_mul_f32_e32 v167, 0x3fb8aa3b, v167
.Lfox_loop:
	s_cmp_eq_u32 s16, s15
	s_cbranch_scc1 .Lfox_diag0
	s_add_i32 s18, s16, 1
	s_min_u32 s18, s18, s15
	s_add_i32 s19, s16, 2
	s_min_u32 s19, s19, s15
	s_lshl_b32 s17, s18, 12
	v_add_u32_e32 v183, s17, v162
	global_load_dwordx4 v[78:81], v183, s[6:7]
	global_load_dwordx4 v[82:85], v183, s[6:7] offset:1024
	global_load_dwordx4 v[86:89], v183, s[6:7] offset:2048
	global_load_dwordx4 v[90:93], v183, s[6:7] offset:3072
	s_lshl_b32 s17, s19, 12
	v_add_u32_e32 v183, s17, v162
	global_load_dwordx4 v[42:45], v183, s[4:5]
	global_load_dwordx4 v[46:49], v183, s[4:5] offset:1024
	global_load_dwordx4 v[50:53], v183, s[4:5] offset:2048
	global_load_dwordx4 v[54:57], v183, s[4:5] offset:3072
	s_lshl_b32 s17, s19, 9
	v_add_u32_e32 v183, s17, v190
	s_mov_b64 exec, s[44:45]
	global_load_dwordx4 v[58:61], v183, s[8:9]
	s_mov_b64 exec, -1
	s_waitcnt vmcnt(18)
	v_mfma_f32_32x32x16_bf16 v[146:161], v[2:5], v[94:97], 0
	v_mfma_f32_32x32x16_bf16 v[146:161], v[6:9], v[98:101], v[146:161]
	v_mfma_f32_32x32x16_bf16 v[146:161], v[10:13], v[102:105], v[146:161]
	v_mfma_f32_32x32x16_bf16 v[146:161], v[14:17], v[106:109], v[146:161]
	v_mfma_f32_32x32x16_bf16 v[146:161], v[18:21], v[110:113], v[146:161]
	s_nop 7
	s_nop 4
	v_max3_f32 v183, v146, v147, v148
	v_max3_f32 v184, v149, v150, v151
	v_max3_f32 v185, v152, v153, v154
	v_max3_f32 v186, v155, v156, v157
	v_max3_f32 v187, v158, v159, v160
	v_max3_f32 v183, v183, v184, v185
	v_max3_f32 v186, v186, v187, v161
	v_max_f32_e32 v183, v183, v186
	ds_bpermute_b32 v184, v192, v183
	s_waitcnt lgkmcnt(0)
	v_max_f32_e32 v183, v183, v184
	v_fma_f32 v183, v183, s14, v167
	v_max_f32_e32 v184, v165, v183
	v_sub_f32_e32 v186, v165, v184
	v_exp_f32_e32 v186, v186
	v_mov_b32_e32 v165, v184
	v_sub_f32_e32 v168, v167, v184
	v_fma_f32 v146, v146, s14, v168
	v_exp_f32_e32 v146, v146
	v_fma_f32 v147, v147, s14, v168
	v_exp_f32_e32 v147, v147
	v_fma_f32 v148, v148, s14, v168
	v_exp_f32_e32 v148, v148
	v_fma_f32 v149, v149, s14, v168
	v_exp_f32_e32 v149, v149
	v_fma_f32 v150, v150, s14, v168
	v_exp_f32_e32 v150, v150
	v_fma_f32 v151, v151, s14, v168
	v_exp_f32_e32 v151, v151
	v_fma_f32 v152, v152, s14, v168
	v_exp_f32_e32 v152, v152
	v_fma_f32 v153, v153, s14, v168
	v_exp_f32_e32 v153, v153
	v_fma_f32 v154, v154, s14, v168
	v_exp_f32_e32 v154, v154
	v_fma_f32 v155, v155, s14, v168
	v_exp_f32_e32 v155, v155
	v_fma_f32 v156, v156, s14, v168
	v_exp_f32_e32 v156, v156
	v_fma_f32 v157, v157, s14, v168
	v_exp_f32_e32 v157, v157
	v_fma_f32 v158, v158, s14, v168
	v_exp_f32_e32 v158, v158
	v_fma_f32 v159, v159, s14, v168
	v_exp_f32_e32 v159, v159
	v_fma_f32 v160, v160, s14, v168
	v_exp_f32_e32 v160, v160
	v_fma_f32 v161, v161, s14, v168
	v_exp_f32_e32 v161, v161
	v_mul_f32_e32 v166, v166, v186
	v_pk_mul_f32 v[114:115], v[114:115], v[186:187] op_sel_hi:[1,0]
	v_pk_mul_f32 v[116:117], v[116:117], v[186:187] op_sel_hi:[1,0]
	v_pk_mul_f32 v[118:119], v[118:119], v[186:187] op_sel_hi:[1,0]
	v_pk_mul_f32 v[120:121], v[120:121], v[186:187] op_sel_hi:[1,0]
	v_pk_mul_f32 v[122:123], v[122:123], v[186:187] op_sel_hi:[1,0]
	v_pk_mul_f32 v[124:125], v[124:125], v[186:187] op_sel_hi:[1,0]
	v_pk_mul_f32 v[126:127], v[126:127], v[186:187] op_sel_hi:[1,0]
	v_pk_mul_f32 v[128:129], v[128:129], v[186:187] op_sel_hi:[1,0]
	v_pk_mul_f32 v[130:131], v[130:131], v[186:187] op_sel_hi:[1,0]
	v_pk_mul_f32 v[132:133], v[132:133], v[186:187] op_sel_hi:[1,0]
	v_pk_mul_f32 v[134:135], v[134:135], v[186:187] op_sel_hi:[1,0]
	v_pk_mul_f32 v[136:137], v[136:137], v[186:187] op_sel_hi:[1,0]
	v_pk_mul_f32 v[138:139], v[138:139], v[186:187] op_sel_hi:[1,0]
	v_pk_mul_f32 v[140:141], v[140:141], v[186:187] op_sel_hi:[1,0]
	v_pk_mul_f32 v[142:143], v[142:143], v[186:187] op_sel_hi:[1,0]
	v_pk_mul_f32 v[144:145], v[144:145], v[186:187] op_sel_hi:[1,0]
	v_add_f32_e32 v183, v146, v147
	v_add_f32_e32 v184, v148, v149
	v_add_f32_e32 v185, v150, v151
	v_add_f32_e32 v188, v152, v153
	v_add_f32_e32 v183, v183, v154
	v_add_f32_e32 v184, v184, v155
	v_add_f32_e32 v185, v185, v156
	v_add_f32_e32 v188, v188, v157
	v_add_f32_e32 v183, v183, v158
	v_add_f32_e32 v184, v184, v159
	v_add_f32_e32 v185, v185, v160
	v_add_f32_e32 v188, v188, v161
	v_add_f32_e32 v183, v183, v184
	v_add_f32_e32 v185, v185, v188
	v_add_f32_e32 v183, v183, v185
	v_add_f32_e32 v166, v166, v183
	v_cvt_pk_bf16_f32 v146, v146, v147
	v_cvt_pk_bf16_f32 v147, v148, v149
	v_cvt_pk_bf16_f32 v148, v150, v151
	v_cvt_pk_bf16_f32 v149, v152, v153
	v_cvt_pk_bf16_f32 v150, v154, v155
	v_cvt_pk_bf16_f32 v151, v156, v157
	v_cvt_pk_bf16_f32 v152, v158, v159
	v_cvt_pk_bf16_f32 v153, v160, v161
	s_waitcnt vmcnt(14)
	s_nop 1
	v_mfma_f32_32x32x16_bf16 v[114:129], v[62:65], v[146:149], v[114:129]
	v_mfma_f32_32x32x16_bf16 v[130:145], v[70:73], v[146:149], v[130:145]
	v_mfma_f32_32x32x16_bf16 v[114:129], v[66:69], v[150:153], v[114:129]
	v_mfma_f32_32x32x16_bf16 v[130:145], v[74:77], v[150:153], v[130:145]
	s_add_i32 s16, s16, 1
	s_cmp_eq_u32 s16, s15
	s_cbranch_scc1 .Lfox_diag1
	s_add_i32 s18, s16, 1
	s_min_u32 s18, s18, s15
	s_add_i32 s19, s16, 2
	s_min_u32 s19, s19, s15
	s_lshl_b32 s17, s18, 12
	v_add_u32_e32 v183, s17, v162
	global_load_dwordx4 v[62:65], v183, s[6:7]
	global_load_dwordx4 v[66:69], v183, s[6:7] offset:1024
	global_load_dwordx4 v[70:73], v183, s[6:7] offset:2048
	global_load_dwordx4 v[74:77], v183, s[6:7] offset:3072
	s_lshl_b32 s17, s19, 12
	v_add_u32_e32 v183, s17, v162
	global_load_dwordx4 v[2:5], v183, s[4:5]
	global_load_dwordx4 v[6:9], v183, s[4:5] offset:1024
	global_load_dwordx4 v[10:13], v183, s[4:5] offset:2048
	global_load_dwordx4 v[14:17], v183, s[4:5] offset:3072
	s_lshl_b32 s17, s19, 9
	v_add_u32_e32 v183, s17, v190
	s_mov_b64 exec, s[44:45]
	global_load_dwordx4 v[18:21], v183, s[8:9]
	s_mov_b64 exec, -1
	s_waitcnt vmcnt(18)
	v_mfma_f32_32x32x16_bf16 v[146:161], v[22:25], v[94:97], 0
	v_mfma_f32_32x32x16_bf16 v[146:161], v[26:29], v[98:101], v[146:161]
	v_mfma_f32_32x32x16_bf16 v[146:161], v[30:33], v[102:105], v[146:161]
	v_mfma_f32_32x32x16_bf16 v[146:161], v[34:37], v[106:109], v[146:161]
	v_mfma_f32_32x32x16_bf16 v[146:161], v[38:41], v[110:113], v[146:161]
	s_nop 7
	s_nop 4
	v_max3_f32 v183, v146, v147, v148
	v_max3_f32 v184, v149, v150, v151
	v_max3_f32 v185, v152, v153, v154
	v_max3_f32 v186, v155, v156, v157
	v_max3_f32 v187, v158, v159, v160
	v_max3_f32 v183, v183, v184, v185
	v_max3_f32 v186, v186, v187, v161
	v_max_f32_e32 v183, v183, v186
	ds_bpermute_b32 v184, v192, v183
	s_waitcnt lgkmcnt(0)
	v_max_f32_e32 v183, v183, v184
	v_fma_f32 v183, v183, s14, v167
	v_max_f32_e32 v184, v165, v183
	v_sub_f32_e32 v186, v165, v184
	v_exp_f32_e32 v186, v186
	v_mov_b32_e32 v165, v184
	v_sub_f32_e32 v168, v167, v184
	v_fma_f32 v146, v146, s14, v168
	v_exp_f32_e32 v146, v146
	v_fma_f32 v147, v147, s14, v168
	v_exp_f32_e32 v147, v147
	v_fma_f32 v148, v148, s14, v168
	v_exp_f32_e32 v148, v148
	v_fma_f32 v149, v149, s14, v168
	v_exp_f32_e32 v149, v149
	v_fma_f32 v150, v150, s14, v168
	v_exp_f32_e32 v150, v150
	v_fma_f32 v151, v151, s14, v168
	v_exp_f32_e32 v151, v151
	v_fma_f32 v152, v152, s14, v168
	v_exp_f32_e32 v152, v152
	v_fma_f32 v153, v153, s14, v168
	v_exp_f32_e32 v153, v153
	v_fma_f32 v154, v154, s14, v168
	v_exp_f32_e32 v154, v154
	v_fma_f32 v155, v155, s14, v168
	v_exp_f32_e32 v155, v155
	v_fma_f32 v156, v156, s14, v168
	v_exp_f32_e32 v156, v156
	v_fma_f32 v157, v157, s14, v168
	v_exp_f32_e32 v157, v157
	v_fma_f32 v158, v158, s14, v168
	v_exp_f32_e32 v158, v158
	v_fma_f32 v159, v159, s14, v168
	v_exp_f32_e32 v159, v159
	v_fma_f32 v160, v160, s14, v168
	v_exp_f32_e32 v160, v160
	v_fma_f32 v161, v161, s14, v168
	v_exp_f32_e32 v161, v161
	v_mul_f32_e32 v166, v166, v186
	v_pk_mul_f32 v[114:115], v[114:115], v[186:187] op_sel_hi:[1,0]
	v_pk_mul_f32 v[116:117], v[116:117], v[186:187] op_sel_hi:[1,0]
	v_pk_mul_f32 v[118:119], v[118:119], v[186:187] op_sel_hi:[1,0]
	v_pk_mul_f32 v[120:121], v[120:121], v[186:187] op_sel_hi:[1,0]
	v_pk_mul_f32 v[122:123], v[122:123], v[186:187] op_sel_hi:[1,0]
	v_pk_mul_f32 v[124:125], v[124:125], v[186:187] op_sel_hi:[1,0]
	v_pk_mul_f32 v[126:127], v[126:127], v[186:187] op_sel_hi:[1,0]
	v_pk_mul_f32 v[128:129], v[128:129], v[186:187] op_sel_hi:[1,0]
	v_pk_mul_f32 v[130:131], v[130:131], v[186:187] op_sel_hi:[1,0]
	v_pk_mul_f32 v[132:133], v[132:133], v[186:187] op_sel_hi:[1,0]
	v_pk_mul_f32 v[134:135], v[134:135], v[186:187] op_sel_hi:[1,0]
	v_pk_mul_f32 v[136:137], v[136:137], v[186:187] op_sel_hi:[1,0]
	v_pk_mul_f32 v[138:139], v[138:139], v[186:187] op_sel_hi:[1,0]
	v_pk_mul_f32 v[140:141], v[140:141], v[186:187] op_sel_hi:[1,0]
	v_pk_mul_f32 v[142:143], v[142:143], v[186:187] op_sel_hi:[1,0]
	v_pk_mul_f32 v[144:145], v[144:145], v[186:187] op_sel_hi:[1,0]
	v_add_f32_e32 v183, v146, v147
	v_add_f32_e32 v184, v148, v149
	v_add_f32_e32 v185, v150, v151
	v_add_f32_e32 v188, v152, v153
	v_add_f32_e32 v183, v183, v154
	v_add_f32_e32 v184, v184, v155
	v_add_f32_e32 v185, v185, v156
	v_add_f32_e32 v188, v188, v157
	v_add_f32_e32 v183, v183, v158
	v_add_f32_e32 v184, v184, v159
	v_add_f32_e32 v185, v185, v160
	v_add_f32_e32 v188, v188, v161
	v_add_f32_e32 v183, v183, v184
	v_add_f32_e32 v185, v185, v188
	v_add_f32_e32 v183, v183, v185
	v_add_f32_e32 v166, v166, v183
	v_cvt_pk_bf16_f32 v146, v146, v147
	v_cvt_pk_bf16_f32 v147, v148, v149
	v_cvt_pk_bf16_f32 v148, v150, v151
	v_cvt_pk_bf16_f32 v149, v152, v153
	v_cvt_pk_bf16_f32 v150, v154, v155
	v_cvt_pk_bf16_f32 v151, v156, v157
	v_cvt_pk_bf16_f32 v152, v158, v159
	v_cvt_pk_bf16_f32 v153, v160, v161
	s_waitcnt vmcnt(14)
	s_nop 1
	v_mfma_f32_32x32x16_bf16 v[114:129], v[78:81], v[146:149], v[114:129]
	v_mfma_f32_32x32x16_bf16 v[130:145], v[86:89], v[146:149], v[130:145]
	v_mfma_f32_32x32x16_bf16 v[114:129], v[82:85], v[150:153], v[114:129]
	v_mfma_f32_32x32x16_bf16 v[130:145], v[90:93], v[150:153], v[130:145]
	s_add_i32 s16, s16, 1
	s_cmp_eq_u32 s16, s15
	s_cbranch_scc1 .Lfox_diag2
	s_add_i32 s18, s16, 1
	s_min_u32 s18, s18, s15
	s_add_i32 s19, s16, 2
	s_min_u32 s19, s19, s15
	s_lshl_b32 s17, s18, 12
	v_add_u32_e32 v183, s17, v162
	global_load_dwordx4 v[78:81], v183, s[6:7]
	global_load_dwordx4 v[82:85], v183, s[6:7] offset:1024
	global_load_dwordx4 v[86:89], v183, s[6:7] offset:2048
	global_load_dwordx4 v[90:93], v183, s[6:7] offset:3072
	s_lshl_b32 s17, s19, 12
	v_add_u32_e32 v183, s17, v162
	global_load_dwordx4 v[22:25], v183, s[4:5]
	global_load_dwordx4 v[26:29], v183, s[4:5] offset:1024
	global_load_dwordx4 v[30:33], v183, s[4:5] offset:2048
	global_load_dwordx4 v[34:37], v183, s[4:5] offset:3072
	s_lshl_b32 s17, s19, 9
	v_add_u32_e32 v183, s17, v190
	s_mov_b64 exec, s[44:45]
	global_load_dwordx4 v[38:41], v183, s[8:9]
	s_mov_b64 exec, -1
	s_waitcnt vmcnt(18)
	v_mfma_f32_32x32x16_bf16 v[146:161], v[42:45], v[94:97], 0
	v_mfma_f32_32x32x16_bf16 v[146:161], v[46:49], v[98:101], v[146:161]
	v_mfma_f32_32x32x16_bf16 v[146:161], v[50:53], v[102:105], v[146:161]
	v_mfma_f32_32x32x16_bf16 v[146:161], v[54:57], v[106:109], v[146:161]
	v_mfma_f32_32x32x16_bf16 v[146:161], v[58:61], v[110:113], v[146:161]
	s_nop 7
	s_nop 4
	v_max3_f32 v183, v146, v147, v148
	v_max3_f32 v184, v149, v150, v151
	v_max3_f32 v185, v152, v153, v154
	v_max3_f32 v186, v155, v156, v157
	v_max3_f32 v187, v158, v159, v160
	v_max3_f32 v183, v183, v184, v185
	v_max3_f32 v186, v186, v187, v161
	v_max_f32_e32 v183, v183, v186
	ds_bpermute_b32 v184, v192, v183
	s_waitcnt lgkmcnt(0)
	v_max_f32_e32 v183, v183, v184
	v_fma_f32 v183, v183, s14, v167
	v_max_f32_e32 v184, v165, v183
	v_sub_f32_e32 v186, v165, v184
	v_exp_f32_e32 v186, v186
	v_mov_b32_e32 v165, v184
	v_sub_f32_e32 v168, v167, v184
	v_fma_f32 v146, v146, s14, v168
	v_exp_f32_e32 v146, v146
	v_fma_f32 v147, v147, s14, v168
	v_exp_f32_e32 v147, v147
	v_fma_f32 v148, v148, s14, v168
	v_exp_f32_e32 v148, v148
	v_fma_f32 v149, v149, s14, v168
	v_exp_f32_e32 v149, v149
	v_fma_f32 v150, v150, s14, v168
	v_exp_f32_e32 v150, v150
	v_fma_f32 v151, v151, s14, v168
	v_exp_f32_e32 v151, v151
	v_fma_f32 v152, v152, s14, v168
	v_exp_f32_e32 v152, v152
	v_fma_f32 v153, v153, s14, v168
	v_exp_f32_e32 v153, v153
	v_fma_f32 v154, v154, s14, v168
	v_exp_f32_e32 v154, v154
	v_fma_f32 v155, v155, s14, v168
	v_exp_f32_e32 v155, v155
	v_fma_f32 v156, v156, s14, v168
	v_exp_f32_e32 v156, v156
	v_fma_f32 v157, v157, s14, v168
	v_exp_f32_e32 v157, v157
	v_fma_f32 v158, v158, s14, v168
	v_exp_f32_e32 v158, v158
	v_fma_f32 v159, v159, s14, v168
	v_exp_f32_e32 v159, v159
	v_fma_f32 v160, v160, s14, v168
	v_exp_f32_e32 v160, v160
	v_fma_f32 v161, v161, s14, v168
	v_exp_f32_e32 v161, v161
	v_mul_f32_e32 v166, v166, v186
	v_pk_mul_f32 v[114:115], v[114:115], v[186:187] op_sel_hi:[1,0]
	v_pk_mul_f32 v[116:117], v[116:117], v[186:187] op_sel_hi:[1,0]
	v_pk_mul_f32 v[118:119], v[118:119], v[186:187] op_sel_hi:[1,0]
	v_pk_mul_f32 v[120:121], v[120:121], v[186:187] op_sel_hi:[1,0]
	v_pk_mul_f32 v[122:123], v[122:123], v[186:187] op_sel_hi:[1,0]
	v_pk_mul_f32 v[124:125], v[124:125], v[186:187] op_sel_hi:[1,0]
	v_pk_mul_f32 v[126:127], v[126:127], v[186:187] op_sel_hi:[1,0]
	v_pk_mul_f32 v[128:129], v[128:129], v[186:187] op_sel_hi:[1,0]
	v_pk_mul_f32 v[130:131], v[130:131], v[186:187] op_sel_hi:[1,0]
	v_pk_mul_f32 v[132:133], v[132:133], v[186:187] op_sel_hi:[1,0]
	v_pk_mul_f32 v[134:135], v[134:135], v[186:187] op_sel_hi:[1,0]
	v_pk_mul_f32 v[136:137], v[136:137], v[186:187] op_sel_hi:[1,0]
	v_pk_mul_f32 v[138:139], v[138:139], v[186:187] op_sel_hi:[1,0]
	v_pk_mul_f32 v[140:141], v[140:141], v[186:187] op_sel_hi:[1,0]
	v_pk_mul_f32 v[142:143], v[142:143], v[186:187] op_sel_hi:[1,0]
	v_pk_mul_f32 v[144:145], v[144:145], v[186:187] op_sel_hi:[1,0]
	v_add_f32_e32 v183, v146, v147
	v_add_f32_e32 v184, v148, v149
	v_add_f32_e32 v185, v150, v151
	v_add_f32_e32 v188, v152, v153
	v_add_f32_e32 v183, v183, v154
	v_add_f32_e32 v184, v184, v155
	v_add_f32_e32 v185, v185, v156
	v_add_f32_e32 v188, v188, v157
	v_add_f32_e32 v183, v183, v158
	v_add_f32_e32 v184, v184, v159
	v_add_f32_e32 v185, v185, v160
	v_add_f32_e32 v188, v188, v161
	v_add_f32_e32 v183, v183, v184
	v_add_f32_e32 v185, v185, v188
	v_add_f32_e32 v183, v183, v185
	v_add_f32_e32 v166, v166, v183
	v_cvt_pk_bf16_f32 v146, v146, v147
	v_cvt_pk_bf16_f32 v147, v148, v149
	v_cvt_pk_bf16_f32 v148, v150, v151
	v_cvt_pk_bf16_f32 v149, v152, v153
	v_cvt_pk_bf16_f32 v150, v154, v155
	v_cvt_pk_bf16_f32 v151, v156, v157
	v_cvt_pk_bf16_f32 v152, v158, v159
	v_cvt_pk_bf16_f32 v153, v160, v161
	s_waitcnt vmcnt(14)
	s_nop 1
	v_mfma_f32_32x32x16_bf16 v[114:129], v[62:65], v[146:149], v[114:129]
	v_mfma_f32_32x32x16_bf16 v[130:145], v[70:73], v[146:149], v[130:145]
	v_mfma_f32_32x32x16_bf16 v[114:129], v[66:69], v[150:153], v[114:129]
	v_mfma_f32_32x32x16_bf16 v[130:145], v[74:77], v[150:153], v[130:145]
	s_add_i32 s16, s16, 1
	s_cmp_eq_u32 s16, s15
	s_cbranch_scc1 .Lfox_diag3
	s_add_i32 s18, s16, 1
	s_min_u32 s18, s18, s15
	s_add_i32 s19, s16, 2
	s_min_u32 s19, s19, s15
	s_lshl_b32 s17, s18, 12
	v_add_u32_e32 v183, s17, v162
	global_load_dwordx4 v[62:65], v183, s[6:7]
	global_load_dwordx4 v[66:69], v183, s[6:7] offset:1024
	global_load_dwordx4 v[70:73], v183, s[6:7] offset:2048
	global_load_dwordx4 v[74:77], v183, s[6:7] offset:3072
	s_lshl_b32 s17, s19, 12
	v_add_u32_e32 v183, s17, v162
	global_load_dwordx4 v[42:45], v183, s[4:5]
	global_load_dwordx4 v[46:49], v183, s[4:5] offset:1024
	global_load_dwordx4 v[50:53], v183, s[4:5] offset:2048
	global_load_dwordx4 v[54:57], v183, s[4:5] offset:3072
	s_lshl_b32 s17, s19, 9
	v_add_u32_e32 v183, s17, v190
	s_mov_b64 exec, s[44:45]
	global_load_dwordx4 v[58:61], v183, s[8:9]
	s_mov_b64 exec, -1
	s_waitcnt vmcnt(18)
	v_mfma_f32_32x32x16_bf16 v[146:161], v[2:5], v[94:97], 0
	v_mfma_f32_32x32x16_bf16 v[146:161], v[6:9], v[98:101], v[146:161]
	v_mfma_f32_32x32x16_bf16 v[146:161], v[10:13], v[102:105], v[146:161]
	v_mfma_f32_32x32x16_bf16 v[146:161], v[14:17], v[106:109], v[146:161]
	v_mfma_f32_32x32x16_bf16 v[146:161], v[18:21], v[110:113], v[146:161]
	s_nop 7
	s_nop 4
	v_max3_f32 v183, v146, v147, v148
	v_max3_f32 v184, v149, v150, v151
	v_max3_f32 v185, v152, v153, v154
	v_max3_f32 v186, v155, v156, v157
	v_max3_f32 v187, v158, v159, v160
	v_max3_f32 v183, v183, v184, v185
	v_max3_f32 v186, v186, v187, v161
	v_max_f32_e32 v183, v183, v186
	ds_bpermute_b32 v184, v192, v183
	s_waitcnt lgkmcnt(0)
	v_max_f32_e32 v183, v183, v184
	v_fma_f32 v183, v183, s14, v167
	v_max_f32_e32 v184, v165, v183
	v_sub_f32_e32 v186, v165, v184
	v_exp_f32_e32 v186, v186
	v_mov_b32_e32 v165, v184
	v_sub_f32_e32 v168, v167, v184
	v_fma_f32 v146, v146, s14, v168
	v_exp_f32_e32 v146, v146
	v_fma_f32 v147, v147, s14, v168
	v_exp_f32_e32 v147, v147
	v_fma_f32 v148, v148, s14, v168
	v_exp_f32_e32 v148, v148
	v_fma_f32 v149, v149, s14, v168
	v_exp_f32_e32 v149, v149
	v_fma_f32 v150, v150, s14, v168
	v_exp_f32_e32 v150, v150
	v_fma_f32 v151, v151, s14, v168
	v_exp_f32_e32 v151, v151
	v_fma_f32 v152, v152, s14, v168
	v_exp_f32_e32 v152, v152
	v_fma_f32 v153, v153, s14, v168
	v_exp_f32_e32 v153, v153
	v_fma_f32 v154, v154, s14, v168
	v_exp_f32_e32 v154, v154
	v_fma_f32 v155, v155, s14, v168
	v_exp_f32_e32 v155, v155
	v_fma_f32 v156, v156, s14, v168
	v_exp_f32_e32 v156, v156
	v_fma_f32 v157, v157, s14, v168
	v_exp_f32_e32 v157, v157
	v_fma_f32 v158, v158, s14, v168
	v_exp_f32_e32 v158, v158
	v_fma_f32 v159, v159, s14, v168
	v_exp_f32_e32 v159, v159
	v_fma_f32 v160, v160, s14, v168
	v_exp_f32_e32 v160, v160
	v_fma_f32 v161, v161, s14, v168
	v_exp_f32_e32 v161, v161
	v_mul_f32_e32 v166, v166, v186
	v_pk_mul_f32 v[114:115], v[114:115], v[186:187] op_sel_hi:[1,0]
	v_pk_mul_f32 v[116:117], v[116:117], v[186:187] op_sel_hi:[1,0]
	v_pk_mul_f32 v[118:119], v[118:119], v[186:187] op_sel_hi:[1,0]
	v_pk_mul_f32 v[120:121], v[120:121], v[186:187] op_sel_hi:[1,0]
	v_pk_mul_f32 v[122:123], v[122:123], v[186:187] op_sel_hi:[1,0]
	v_pk_mul_f32 v[124:125], v[124:125], v[186:187] op_sel_hi:[1,0]
	v_pk_mul_f32 v[126:127], v[126:127], v[186:187] op_sel_hi:[1,0]
	v_pk_mul_f32 v[128:129], v[128:129], v[186:187] op_sel_hi:[1,0]
	v_pk_mul_f32 v[130:131], v[130:131], v[186:187] op_sel_hi:[1,0]
	v_pk_mul_f32 v[132:133], v[132:133], v[186:187] op_sel_hi:[1,0]
	v_pk_mul_f32 v[134:135], v[134:135], v[186:187] op_sel_hi:[1,0]
	v_pk_mul_f32 v[136:137], v[136:137], v[186:187] op_sel_hi:[1,0]
	v_pk_mul_f32 v[138:139], v[138:139], v[186:187] op_sel_hi:[1,0]
	v_pk_mul_f32 v[140:141], v[140:141], v[186:187] op_sel_hi:[1,0]
	v_pk_mul_f32 v[142:143], v[142:143], v[186:187] op_sel_hi:[1,0]
	v_pk_mul_f32 v[144:145], v[144:145], v[186:187] op_sel_hi:[1,0]
	v_add_f32_e32 v183, v146, v147
	v_add_f32_e32 v184, v148, v149
	v_add_f32_e32 v185, v150, v151
	v_add_f32_e32 v188, v152, v153
	v_add_f32_e32 v183, v183, v154
	v_add_f32_e32 v184, v184, v155
	v_add_f32_e32 v185, v185, v156
	v_add_f32_e32 v188, v188, v157
	v_add_f32_e32 v183, v183, v158
	v_add_f32_e32 v184, v184, v159
	v_add_f32_e32 v185, v185, v160
	v_add_f32_e32 v188, v188, v161
	v_add_f32_e32 v183, v183, v184
	v_add_f32_e32 v185, v185, v188
	v_add_f32_e32 v183, v183, v185
	v_add_f32_e32 v166, v166, v183
	v_cvt_pk_bf16_f32 v146, v146, v147
	v_cvt_pk_bf16_f32 v147, v148, v149
	v_cvt_pk_bf16_f32 v148, v150, v151
	v_cvt_pk_bf16_f32 v149, v152, v153
	v_cvt_pk_bf16_f32 v150, v154, v155
	v_cvt_pk_bf16_f32 v151, v156, v157
	v_cvt_pk_bf16_f32 v152, v158, v159
	v_cvt_pk_bf16_f32 v153, v160, v161
	s_waitcnt vmcnt(14)
	s_nop 1
	v_mfma_f32_32x32x16_bf16 v[114:129], v[78:81], v[146:149], v[114:129]
	v_mfma_f32_32x32x16_bf16 v[130:145], v[86:89], v[146:149], v[130:145]
	v_mfma_f32_32x32x16_bf16 v[114:129], v[82:85], v[150:153], v[114:129]
	v_mfma_f32_32x32x16_bf16 v[130:145], v[90:93], v[150:153], v[130:145]
	s_add_i32 s16, s16, 1
	s_cmp_eq_u32 s16, s15
	s_cbranch_scc1 .Lfox_diag4
	s_add_i32 s18, s16, 1
	s_min_u32 s18, s18, s15
	s_add_i32 s19, s16, 2
	s_min_u32 s19, s19, s15
	s_lshl_b32 s17, s18, 12
	v_add_u32_e32 v183, s17, v162
	global_load_dwordx4 v[78:81], v183, s[6:7]
	global_load_dwordx4 v[82:85], v183, s[6:7] offset:1024
	global_load_dwordx4 v[86:89], v183, s[6:7] offset:2048
	global_load_dwordx4 v[90:93], v183, s[6:7] offset:3072
	s_lshl_b32 s17, s19, 12
	v_add_u32_e32 v183, s17, v162
	global_load_dwordx4 v[2:5], v183, s[4:5]
	global_load_dwordx4 v[6:9], v183, s[4:5] offset:1024
	global_load_dwordx4 v[10:13], v183, s[4:5] offset:2048
	global_load_dwordx4 v[14:17], v183, s[4:5] offset:3072
	s_lshl_b32 s17, s19, 9
	v_add_u32_e32 v183, s17, v190
	s_mov_b64 exec, s[44:45]
	global_load_dwordx4 v[18:21], v183, s[8:9]
	s_mov_b64 exec, -1
	s_waitcnt vmcnt(18)
	v_mfma_f32_32x32x16_bf16 v[146:161], v[22:25], v[94:97], 0
	v_mfma_f32_32x32x16_bf16 v[146:161], v[26:29], v[98:101], v[146:161]
	v_mfma_f32_32x32x16_bf16 v[146:161], v[30:33], v[102:105], v[146:161]
	v_mfma_f32_32x32x16_bf16 v[146:161], v[34:37], v[106:109], v[146:161]
	v_mfma_f32_32x32x16_bf16 v[146:161], v[38:41], v[110:113], v[146:161]
	s_nop 7
	s_nop 4
	v_max3_f32 v183, v146, v147, v148
	v_max3_f32 v184, v149, v150, v151
	v_max3_f32 v185, v152, v153, v154
	v_max3_f32 v186, v155, v156, v157
	v_max3_f32 v187, v158, v159, v160
	v_max3_f32 v183, v183, v184, v185
	v_max3_f32 v186, v186, v187, v161
	v_max_f32_e32 v183, v183, v186
	ds_bpermute_b32 v184, v192, v183
	s_waitcnt lgkmcnt(0)
	v_max_f32_e32 v183, v183, v184
	v_fma_f32 v183, v183, s14, v167
	v_max_f32_e32 v184, v165, v183
	v_sub_f32_e32 v186, v165, v184
	v_exp_f32_e32 v186, v186
	v_mov_b32_e32 v165, v184
	v_sub_f32_e32 v168, v167, v184
	v_fma_f32 v146, v146, s14, v168
	v_exp_f32_e32 v146, v146
	v_fma_f32 v147, v147, s14, v168
	v_exp_f32_e32 v147, v147
	v_fma_f32 v148, v148, s14, v168
	v_exp_f32_e32 v148, v148
	v_fma_f32 v149, v149, s14, v168
	v_exp_f32_e32 v149, v149
	v_fma_f32 v150, v150, s14, v168
	v_exp_f32_e32 v150, v150
	v_fma_f32 v151, v151, s14, v168
	v_exp_f32_e32 v151, v151
	v_fma_f32 v152, v152, s14, v168
	v_exp_f32_e32 v152, v152
	v_fma_f32 v153, v153, s14, v168
	v_exp_f32_e32 v153, v153
	v_fma_f32 v154, v154, s14, v168
	v_exp_f32_e32 v154, v154
	v_fma_f32 v155, v155, s14, v168
	v_exp_f32_e32 v155, v155
	v_fma_f32 v156, v156, s14, v168
	v_exp_f32_e32 v156, v156
	v_fma_f32 v157, v157, s14, v168
	v_exp_f32_e32 v157, v157
	v_fma_f32 v158, v158, s14, v168
	v_exp_f32_e32 v158, v158
	v_fma_f32 v159, v159, s14, v168
	v_exp_f32_e32 v159, v159
	v_fma_f32 v160, v160, s14, v168
	v_exp_f32_e32 v160, v160
	v_fma_f32 v161, v161, s14, v168
	v_exp_f32_e32 v161, v161
	v_mul_f32_e32 v166, v166, v186
	v_pk_mul_f32 v[114:115], v[114:115], v[186:187] op_sel_hi:[1,0]
	v_pk_mul_f32 v[116:117], v[116:117], v[186:187] op_sel_hi:[1,0]
	v_pk_mul_f32 v[118:119], v[118:119], v[186:187] op_sel_hi:[1,0]
	v_pk_mul_f32 v[120:121], v[120:121], v[186:187] op_sel_hi:[1,0]
	v_pk_mul_f32 v[122:123], v[122:123], v[186:187] op_sel_hi:[1,0]
	v_pk_mul_f32 v[124:125], v[124:125], v[186:187] op_sel_hi:[1,0]
	v_pk_mul_f32 v[126:127], v[126:127], v[186:187] op_sel_hi:[1,0]
	v_pk_mul_f32 v[128:129], v[128:129], v[186:187] op_sel_hi:[1,0]
	v_pk_mul_f32 v[130:131], v[130:131], v[186:187] op_sel_hi:[1,0]
	v_pk_mul_f32 v[132:133], v[132:133], v[186:187] op_sel_hi:[1,0]
	v_pk_mul_f32 v[134:135], v[134:135], v[186:187] op_sel_hi:[1,0]
	v_pk_mul_f32 v[136:137], v[136:137], v[186:187] op_sel_hi:[1,0]
	v_pk_mul_f32 v[138:139], v[138:139], v[186:187] op_sel_hi:[1,0]
	v_pk_mul_f32 v[140:141], v[140:141], v[186:187] op_sel_hi:[1,0]
	v_pk_mul_f32 v[142:143], v[142:143], v[186:187] op_sel_hi:[1,0]
	v_pk_mul_f32 v[144:145], v[144:145], v[186:187] op_sel_hi:[1,0]
	v_add_f32_e32 v183, v146, v147
	v_add_f32_e32 v184, v148, v149
	v_add_f32_e32 v185, v150, v151
	v_add_f32_e32 v188, v152, v153
	v_add_f32_e32 v183, v183, v154
	v_add_f32_e32 v184, v184, v155
	v_add_f32_e32 v185, v185, v156
	v_add_f32_e32 v188, v188, v157
	v_add_f32_e32 v183, v183, v158
	v_add_f32_e32 v184, v184, v159
	v_add_f32_e32 v185, v185, v160
	v_add_f32_e32 v188, v188, v161
	v_add_f32_e32 v183, v183, v184
	v_add_f32_e32 v185, v185, v188
	v_add_f32_e32 v183, v183, v185
	v_add_f32_e32 v166, v166, v183
	v_cvt_pk_bf16_f32 v146, v146, v147
	v_cvt_pk_bf16_f32 v147, v148, v149
	v_cvt_pk_bf16_f32 v148, v150, v151
	v_cvt_pk_bf16_f32 v149, v152, v153
	v_cvt_pk_bf16_f32 v150, v154, v155
	v_cvt_pk_bf16_f32 v151, v156, v157
	v_cvt_pk_bf16_f32 v152, v158, v159
	v_cvt_pk_bf16_f32 v153, v160, v161
	s_waitcnt vmcnt(14)
	s_nop 1
	v_mfma_f32_32x32x16_bf16 v[114:129], v[62:65], v[146:149], v[114:129]
	v_mfma_f32_32x32x16_bf16 v[130:145], v[70:73], v[146:149], v[130:145]
	v_mfma_f32_32x32x16_bf16 v[114:129], v[66:69], v[150:153], v[114:129]
	v_mfma_f32_32x32x16_bf16 v[130:145], v[74:77], v[150:153], v[130:145]
	s_add_i32 s16, s16, 1
	s_cmp_eq_u32 s16, s15
	s_cbranch_scc1 .Lfox_diag5
	s_add_i32 s18, s16, 1
	s_min_u32 s18, s18, s15
	s_add_i32 s19, s16, 2
	s_min_u32 s19, s19, s15
	s_lshl_b32 s17, s18, 12
	v_add_u32_e32 v183, s17, v162
	global_load_dwordx4 v[62:65], v183, s[6:7]
	global_load_dwordx4 v[66:69], v183, s[6:7] offset:1024
	global_load_dwordx4 v[70:73], v183, s[6:7] offset:2048
	global_load_dwordx4 v[74:77], v183, s[6:7] offset:3072
	s_lshl_b32 s17, s19, 12
	v_add_u32_e32 v183, s17, v162
	global_load_dwordx4 v[22:25], v183, s[4:5]
	global_load_dwordx4 v[26:29], v183, s[4:5] offset:1024
	global_load_dwordx4 v[30:33], v183, s[4:5] offset:2048
	global_load_dwordx4 v[34:37], v183, s[4:5] offset:3072
	s_lshl_b32 s17, s19, 9
	v_add_u32_e32 v183, s17, v190
	s_mov_b64 exec, s[44:45]
	global_load_dwordx4 v[38:41], v183, s[8:9]
	s_mov_b64 exec, -1
	s_waitcnt vmcnt(18)
	v_mfma_f32_32x32x16_bf16 v[146:161], v[42:45], v[94:97], 0
	v_mfma_f32_32x32x16_bf16 v[146:161], v[46:49], v[98:101], v[146:161]
	v_mfma_f32_32x32x16_bf16 v[146:161], v[50:53], v[102:105], v[146:161]
	v_mfma_f32_32x32x16_bf16 v[146:161], v[54:57], v[106:109], v[146:161]
	v_mfma_f32_32x32x16_bf16 v[146:161], v[58:61], v[110:113], v[146:161]
	s_nop 7
	s_nop 4
	v_max3_f32 v183, v146, v147, v148
	v_max3_f32 v184, v149, v150, v151
	v_max3_f32 v185, v152, v153, v154
	v_max3_f32 v186, v155, v156, v157
	v_max3_f32 v187, v158, v159, v160
	v_max3_f32 v183, v183, v184, v185
	v_max3_f32 v186, v186, v187, v161
	v_max_f32_e32 v183, v183, v186
	ds_bpermute_b32 v184, v192, v183
	s_waitcnt lgkmcnt(0)
	v_max_f32_e32 v183, v183, v184
	v_fma_f32 v183, v183, s14, v167
	v_max_f32_e32 v184, v165, v183
	v_sub_f32_e32 v186, v165, v184
	v_exp_f32_e32 v186, v186
	v_mov_b32_e32 v165, v184
	v_sub_f32_e32 v168, v167, v184
	v_fma_f32 v146, v146, s14, v168
	v_exp_f32_e32 v146, v146
	v_fma_f32 v147, v147, s14, v168
	v_exp_f32_e32 v147, v147
	v_fma_f32 v148, v148, s14, v168
	v_exp_f32_e32 v148, v148
	v_fma_f32 v149, v149, s14, v168
	v_exp_f32_e32 v149, v149
	v_fma_f32 v150, v150, s14, v168
	v_exp_f32_e32 v150, v150
	v_fma_f32 v151, v151, s14, v168
	v_exp_f32_e32 v151, v151
	v_fma_f32 v152, v152, s14, v168
	v_exp_f32_e32 v152, v152
	v_fma_f32 v153, v153, s14, v168
	v_exp_f32_e32 v153, v153
	v_fma_f32 v154, v154, s14, v168
	v_exp_f32_e32 v154, v154
	v_fma_f32 v155, v155, s14, v168
	v_exp_f32_e32 v155, v155
	v_fma_f32 v156, v156, s14, v168
	v_exp_f32_e32 v156, v156
	v_fma_f32 v157, v157, s14, v168
	v_exp_f32_e32 v157, v157
	v_fma_f32 v158, v158, s14, v168
	v_exp_f32_e32 v158, v158
	v_fma_f32 v159, v159, s14, v168
	v_exp_f32_e32 v159, v159
	v_fma_f32 v160, v160, s14, v168
	v_exp_f32_e32 v160, v160
	v_fma_f32 v161, v161, s14, v168
	v_exp_f32_e32 v161, v161
	v_mul_f32_e32 v166, v166, v186
	v_pk_mul_f32 v[114:115], v[114:115], v[186:187] op_sel_hi:[1,0]
	v_pk_mul_f32 v[116:117], v[116:117], v[186:187] op_sel_hi:[1,0]
	v_pk_mul_f32 v[118:119], v[118:119], v[186:187] op_sel_hi:[1,0]
	v_pk_mul_f32 v[120:121], v[120:121], v[186:187] op_sel_hi:[1,0]
	v_pk_mul_f32 v[122:123], v[122:123], v[186:187] op_sel_hi:[1,0]
	v_pk_mul_f32 v[124:125], v[124:125], v[186:187] op_sel_hi:[1,0]
	v_pk_mul_f32 v[126:127], v[126:127], v[186:187] op_sel_hi:[1,0]
	v_pk_mul_f32 v[128:129], v[128:129], v[186:187] op_sel_hi:[1,0]
	v_pk_mul_f32 v[130:131], v[130:131], v[186:187] op_sel_hi:[1,0]
	v_pk_mul_f32 v[132:133], v[132:133], v[186:187] op_sel_hi:[1,0]
	v_pk_mul_f32 v[134:135], v[134:135], v[186:187] op_sel_hi:[1,0]
	v_pk_mul_f32 v[136:137], v[136:137], v[186:187] op_sel_hi:[1,0]
	v_pk_mul_f32 v[138:139], v[138:139], v[186:187] op_sel_hi:[1,0]
	v_pk_mul_f32 v[140:141], v[140:141], v[186:187] op_sel_hi:[1,0]
	v_pk_mul_f32 v[142:143], v[142:143], v[186:187] op_sel_hi:[1,0]
	v_pk_mul_f32 v[144:145], v[144:145], v[186:187] op_sel_hi:[1,0]
	v_add_f32_e32 v183, v146, v147
	v_add_f32_e32 v184, v148, v149
	v_add_f32_e32 v185, v150, v151
	v_add_f32_e32 v188, v152, v153
	v_add_f32_e32 v183, v183, v154
	v_add_f32_e32 v184, v184, v155
	v_add_f32_e32 v185, v185, v156
	v_add_f32_e32 v188, v188, v157
	v_add_f32_e32 v183, v183, v158
	v_add_f32_e32 v184, v184, v159
	v_add_f32_e32 v185, v185, v160
	v_add_f32_e32 v188, v188, v161
	v_add_f32_e32 v183, v183, v184
	v_add_f32_e32 v185, v185, v188
	v_add_f32_e32 v183, v183, v185
	v_add_f32_e32 v166, v166, v183
	v_cvt_pk_bf16_f32 v146, v146, v147
	v_cvt_pk_bf16_f32 v147, v148, v149
	v_cvt_pk_bf16_f32 v148, v150, v151
	v_cvt_pk_bf16_f32 v149, v152, v153
	v_cvt_pk_bf16_f32 v150, v154, v155
	v_cvt_pk_bf16_f32 v151, v156, v157
	v_cvt_pk_bf16_f32 v152, v158, v159
	v_cvt_pk_bf16_f32 v153, v160, v161
	s_waitcnt vmcnt(14)
	s_nop 1
	v_mfma_f32_32x32x16_bf16 v[114:129], v[78:81], v[146:149], v[114:129]
	v_mfma_f32_32x32x16_bf16 v[130:145], v[86:89], v[146:149], v[130:145]
	v_mfma_f32_32x32x16_bf16 v[114:129], v[82:85], v[150:153], v[114:129]
	v_mfma_f32_32x32x16_bf16 v[130:145], v[90:93], v[150:153], v[130:145]
	s_add_i32 s16, s16, 1
	s_branch .Lfox_loop
.Lfox_diag0:
	s_add_i32 s18, s16, 1
	s_min_u32 s18, s18, s15
	s_add_i32 s19, s16, 2
	s_min_u32 s19, s19, s15
	s_lshl_b32 s17, s18, 12
	v_add_u32_e32 v183, s17, v162
	global_load_dwordx4 v[78:81], v183, s[6:7]
	global_load_dwordx4 v[82:85], v183, s[6:7] offset:1024
	global_load_dwordx4 v[86:89], v183, s[6:7] offset:2048
	global_load_dwordx4 v[90:93], v183, s[6:7] offset:3072
	s_lshl_b32 s17, s19, 12
	v_add_u32_e32 v183, s17, v162
	global_load_dwordx4 v[42:45], v183, s[4:5]
	global_load_dwordx4 v[46:49], v183, s[4:5] offset:1024
	global_load_dwordx4 v[50:53], v183, s[4:5] offset:2048
	global_load_dwordx4 v[54:57], v183, s[4:5] offset:3072
	s_lshl_b32 s17, s19, 9
	v_add_u32_e32 v183, s17, v190
	s_mov_b64 exec, s[44:45]
	global_load_dwordx4 v[58:61], v183, s[8:9]
	s_mov_b64 exec, -1
	s_waitcnt vmcnt(18)
	v_mfma_f32_32x32x16_bf16 v[146:161], v[2:5], v[94:97], 0
	v_mfma_f32_32x32x16_bf16 v[146:161], v[6:9], v[98:101], v[146:161]
	v_mfma_f32_32x32x16_bf16 v[146:161], v[10:13], v[102:105], v[146:161]
	v_mfma_f32_32x32x16_bf16 v[146:161], v[14:17], v[106:109], v[146:161]
	v_mfma_f32_32x32x16_bf16 v[146:161], v[18:21], v[110:113], v[146:161]
	s_nop 7
	s_nop 4
	v_cmp_le_i32_e64 s[34:35], 0, v170
	v_cmp_le_i32_e64 s[36:37], 1, v170
	v_cmp_le_i32_e64 s[38:39], 2, v170
	v_cmp_le_i32_e64 s[40:41], 3, v170
	v_cmp_le_i32_e32 vcc, 8, v170
	v_cndmask_b32_e64 v146, v193, v146, s[34:35]
	v_cndmask_b32_e64 v147, v193, v147, s[36:37]
	v_cndmask_b32_e64 v148, v193, v148, s[38:39]
	v_cndmask_b32_e64 v149, v193, v149, s[40:41]
	v_cndmask_b32_e64 v150, v193, v150, vcc
	v_cmp_le_i32_e64 s[34:35], 9, v170
	v_cmp_le_i32_e64 s[36:37], 10, v170
	v_cmp_le_i32_e64 s[38:39], 11, v170
	v_cmp_le_i32_e64 s[40:41], 16, v170
	v_cmp_le_i32_e32 vcc, 17, v170
	v_cndmask_b32_e64 v151, v193, v151, s[34:35]
	v_cndmask_b32_e64 v152, v193, v152, s[36:37]
	v_cndmask_b32_e64 v153, v193, v153, s[38:39]
	v_cndmask_b32_e64 v154, v193, v154, s[40:41]
	v_cndmask_b32_e64 v155, v193, v155, vcc
	v_cmp_le_i32_e64 s[34:35], 18, v170
	v_cmp_le_i32_e64 s[36:37], 19, v170
	v_cmp_le_i32_e64 s[38:39], 24, v170
	v_cmp_le_i32_e64 s[40:41], 25, v170
	v_cmp_le_i32_e32 vcc, 26, v170
	v_cndmask_b32_e64 v156, v193, v156, s[34:35]
	v_cndmask_b32_e64 v157, v193, v157, s[36:37]
	v_cndmask_b32_e64 v158, v193, v158, s[38:39]
	v_cndmask_b32_e64 v159, v193, v159, s[40:41]
	v_cndmask_b32_e64 v160, v193, v160, vcc
	v_cmp_le_i32_e64 s[34:35], 27, v170
	s_nop 1
	v_cndmask_b32_e64 v161, v193, v161, s[34:35]
	v_max3_f32 v183, v146, v147, v148
	v_max3_f32 v184, v149, v150, v151
	v_max3_f32 v185, v152, v153, v154
	v_max3_f32 v186, v155, v156, v157
	v_max3_f32 v187, v158, v159, v160
	v_max3_f32 v183, v183, v184, v185
	v_max3_f32 v186, v186, v187, v161
	v_max_f32_e32 v183, v183, v186
	ds_bpermute_b32 v184, v192, v183
	s_waitcnt lgkmcnt(0)
	v_max_f32_e32 v183, v183, v184
	v_fma_f32 v183, v183, s14, v167
	v_max_f32_e32 v184, v165, v183
	v_sub_f32_e32 v186, v165, v184
	v_exp_f32_e32 v186, v186
	v_mov_b32_e32 v165, v184
	v_sub_f32_e32 v168, v167, v184
	v_fma_f32 v146, v146, s14, v168
	v_exp_f32_e32 v146, v146
	v_fma_f32 v147, v147, s14, v168
	v_exp_f32_e32 v147, v147
	v_fma_f32 v148, v148, s14, v168
	v_exp_f32_e32 v148, v148
	v_fma_f32 v149, v149, s14, v168
	v_exp_f32_e32 v149, v149
	v_fma_f32 v150, v150, s14, v168
	v_exp_f32_e32 v150, v150
	v_fma_f32 v151, v151, s14, v168
	v_exp_f32_e32 v151, v151
	v_fma_f32 v152, v152, s14, v168
	v_exp_f32_e32 v152, v152
	v_fma_f32 v153, v153, s14, v168
	v_exp_f32_e32 v153, v153
	v_fma_f32 v154, v154, s14, v168
	v_exp_f32_e32 v154, v154
	v_fma_f32 v155, v155, s14, v168
	v_exp_f32_e32 v155, v155
	v_fma_f32 v156, v156, s14, v168
	v_exp_f32_e32 v156, v156
	v_fma_f32 v157, v157, s14, v168
	v_exp_f32_e32 v157, v157
	v_fma_f32 v158, v158, s14, v168
	v_exp_f32_e32 v158, v158
	v_fma_f32 v159, v159, s14, v168
	v_exp_f32_e32 v159, v159
	v_fma_f32 v160, v160, s14, v168
	v_exp_f32_e32 v160, v160
	v_fma_f32 v161, v161, s14, v168
	v_exp_f32_e32 v161, v161
	v_mul_f32_e32 v166, v166, v186
	v_pk_mul_f32 v[114:115], v[114:115], v[186:187] op_sel_hi:[1,0]
	v_pk_mul_f32 v[116:117], v[116:117], v[186:187] op_sel_hi:[1,0]
	v_pk_mul_f32 v[118:119], v[118:119], v[186:187] op_sel_hi:[1,0]
	v_pk_mul_f32 v[120:121], v[120:121], v[186:187] op_sel_hi:[1,0]
	v_pk_mul_f32 v[122:123], v[122:123], v[186:187] op_sel_hi:[1,0]
	v_pk_mul_f32 v[124:125], v[124:125], v[186:187] op_sel_hi:[1,0]
	v_pk_mul_f32 v[126:127], v[126:127], v[186:187] op_sel_hi:[1,0]
	v_pk_mul_f32 v[128:129], v[128:129], v[186:187] op_sel_hi:[1,0]
	v_pk_mul_f32 v[130:131], v[130:131], v[186:187] op_sel_hi:[1,0]
	v_pk_mul_f32 v[132:133], v[132:133], v[186:187] op_sel_hi:[1,0]
	v_pk_mul_f32 v[134:135], v[134:135], v[186:187] op_sel_hi:[1,0]
	v_pk_mul_f32 v[136:137], v[136:137], v[186:187] op_sel_hi:[1,0]
	v_pk_mul_f32 v[138:139], v[138:139], v[186:187] op_sel_hi:[1,0]
	v_pk_mul_f32 v[140:141], v[140:141], v[186:187] op_sel_hi:[1,0]
	v_pk_mul_f32 v[142:143], v[142:143], v[186:187] op_sel_hi:[1,0]
	v_pk_mul_f32 v[144:145], v[144:145], v[186:187] op_sel_hi:[1,0]
	v_add_f32_e32 v183, v146, v147
	v_add_f32_e32 v184, v148, v149
	v_add_f32_e32 v185, v150, v151
	v_add_f32_e32 v188, v152, v153
	v_add_f32_e32 v183, v183, v154
	v_add_f32_e32 v184, v184, v155
	v_add_f32_e32 v185, v185, v156
	v_add_f32_e32 v188, v188, v157
	v_add_f32_e32 v183, v183, v158
	v_add_f32_e32 v184, v184, v159
	v_add_f32_e32 v185, v185, v160
	v_add_f32_e32 v188, v188, v161
	v_add_f32_e32 v183, v183, v184
	v_add_f32_e32 v185, v185, v188
	v_add_f32_e32 v183, v183, v185
	v_add_f32_e32 v166, v166, v183
	v_cvt_pk_bf16_f32 v146, v146, v147
	v_cvt_pk_bf16_f32 v147, v148, v149
	v_cvt_pk_bf16_f32 v148, v150, v151
	v_cvt_pk_bf16_f32 v149, v152, v153
	v_cvt_pk_bf16_f32 v150, v154, v155
	v_cvt_pk_bf16_f32 v151, v156, v157
	v_cvt_pk_bf16_f32 v152, v158, v159
	v_cvt_pk_bf16_f32 v153, v160, v161
	s_waitcnt vmcnt(14)
	s_nop 1
	v_mfma_f32_32x32x16_bf16 v[114:129], v[62:65], v[146:149], v[114:129]
	v_mfma_f32_32x32x16_bf16 v[130:145], v[70:73], v[146:149], v[130:145]
	v_mfma_f32_32x32x16_bf16 v[114:129], v[66:69], v[150:153], v[114:129]
	v_mfma_f32_32x32x16_bf16 v[130:145], v[74:77], v[150:153], v[130:145]
	s_branch .Lfox_epi
.Lfox_diag1:
	s_add_i32 s18, s16, 1
	s_min_u32 s18, s18, s15
	s_add_i32 s19, s16, 2
	s_min_u32 s19, s19, s15
	s_lshl_b32 s17, s18, 12
	v_add_u32_e32 v183, s17, v162
	global_load_dwordx4 v[62:65], v183, s[6:7]
	global_load_dwordx4 v[66:69], v183, s[6:7] offset:1024
	global_load_dwordx4 v[70:73], v183, s[6:7] offset:2048
	global_load_dwordx4 v[74:77], v183, s[6:7] offset:3072
	s_lshl_b32 s17, s19, 12
	v_add_u32_e32 v183, s17, v162
	global_load_dwordx4 v[2:5], v183, s[4:5]
	global_load_dwordx4 v[6:9], v183, s[4:5] offset:1024
	global_load_dwordx4 v[10:13], v183, s[4:5] offset:2048
	global_load_dwordx4 v[14:17], v183, s[4:5] offset:3072
	s_lshl_b32 s17, s19, 9
	v_add_u32_e32 v183, s17, v190
	s_mov_b64 exec, s[44:45]
	global_load_dwordx4 v[18:21], v183, s[8:9]
	s_mov_b64 exec, -1
	s_waitcnt vmcnt(18)
	v_mfma_f32_32x32x16_bf16 v[146:161], v[22:25], v[94:97], 0
	v_mfma_f32_32x32x16_bf16 v[146:161], v[26:29], v[98:101], v[146:161]
	v_mfma_f32_32x32x16_bf16 v[146:161], v[30:33], v[102:105], v[146:161]
	v_mfma_f32_32x32x16_bf16 v[146:161], v[34:37], v[106:109], v[146:161]
	v_mfma_f32_32x32x16_bf16 v[146:161], v[38:41], v[110:113], v[146:161]
	s_nop 7
	s_nop 4
	v_cmp_le_i32_e64 s[34:35], 0, v170
	v_cmp_le_i32_e64 s[36:37], 1, v170
	v_cmp_le_i32_e64 s[38:39], 2, v170
	v_cmp_le_i32_e64 s[40:41], 3, v170
	v_cmp_le_i32_e32 vcc, 8, v170
	v_cndmask_b32_e64 v146, v193, v146, s[34:35]
	v_cndmask_b32_e64 v147, v193, v147, s[36:37]
	v_cndmask_b32_e64 v148, v193, v148, s[38:39]
	v_cndmask_b32_e64 v149, v193, v149, s[40:41]
	v_cndmask_b32_e64 v150, v193, v150, vcc
	v_cmp_le_i32_e64 s[34:35], 9, v170
	v_cmp_le_i32_e64 s[36:37], 10, v170
	v_cmp_le_i32_e64 s[38:39], 11, v170
	v_cmp_le_i32_e64 s[40:41], 16, v170
	v_cmp_le_i32_e32 vcc, 17, v170
	v_cndmask_b32_e64 v151, v193, v151, s[34:35]
	v_cndmask_b32_e64 v152, v193, v152, s[36:37]
	v_cndmask_b32_e64 v153, v193, v153, s[38:39]
	v_cndmask_b32_e64 v154, v193, v154, s[40:41]
	v_cndmask_b32_e64 v155, v193, v155, vcc
	v_cmp_le_i32_e64 s[34:35], 18, v170
	v_cmp_le_i32_e64 s[36:37], 19, v170
	v_cmp_le_i32_e64 s[38:39], 24, v170
	v_cmp_le_i32_e64 s[40:41], 25, v170
	v_cmp_le_i32_e32 vcc, 26, v170
	v_cndmask_b32_e64 v156, v193, v156, s[34:35]
	v_cndmask_b32_e64 v157, v193, v157, s[36:37]
	v_cndmask_b32_e64 v158, v193, v158, s[38:39]
	v_cndmask_b32_e64 v159, v193, v159, s[40:41]
	v_cndmask_b32_e64 v160, v193, v160, vcc
	v_cmp_le_i32_e64 s[34:35], 27, v170
	s_nop 1
	v_cndmask_b32_e64 v161, v193, v161, s[34:35]
	v_max3_f32 v183, v146, v147, v148
	v_max3_f32 v184, v149, v150, v151
	v_max3_f32 v185, v152, v153, v154
	v_max3_f32 v186, v155, v156, v157
	v_max3_f32 v187, v158, v159, v160
	v_max3_f32 v183, v183, v184, v185
	v_max3_f32 v186, v186, v187, v161
	v_max_f32_e32 v183, v183, v186
	ds_bpermute_b32 v184, v192, v183
	s_waitcnt lgkmcnt(0)
	v_max_f32_e32 v183, v183, v184
	v_fma_f32 v183, v183, s14, v167
	v_max_f32_e32 v184, v165, v183
	v_sub_f32_e32 v186, v165, v184
	v_exp_f32_e32 v186, v186
	v_mov_b32_e32 v165, v184
	v_sub_f32_e32 v168, v167, v184
	v_fma_f32 v146, v146, s14, v168
	v_exp_f32_e32 v146, v146
	v_fma_f32 v147, v147, s14, v168
	v_exp_f32_e32 v147, v147
	v_fma_f32 v148, v148, s14, v168
	v_exp_f32_e32 v148, v148
	v_fma_f32 v149, v149, s14, v168
	v_exp_f32_e32 v149, v149
	v_fma_f32 v150, v150, s14, v168
	v_exp_f32_e32 v150, v150
	v_fma_f32 v151, v151, s14, v168
	v_exp_f32_e32 v151, v151
	v_fma_f32 v152, v152, s14, v168
	v_exp_f32_e32 v152, v152
	v_fma_f32 v153, v153, s14, v168
	v_exp_f32_e32 v153, v153
	v_fma_f32 v154, v154, s14, v168
	v_exp_f32_e32 v154, v154
	v_fma_f32 v155, v155, s14, v168
	v_exp_f32_e32 v155, v155
	v_fma_f32 v156, v156, s14, v168
	v_exp_f32_e32 v156, v156
	v_fma_f32 v157, v157, s14, v168
	v_exp_f32_e32 v157, v157
	v_fma_f32 v158, v158, s14, v168
	v_exp_f32_e32 v158, v158
	v_fma_f32 v159, v159, s14, v168
	v_exp_f32_e32 v159, v159
	v_fma_f32 v160, v160, s14, v168
	v_exp_f32_e32 v160, v160
	v_fma_f32 v161, v161, s14, v168
	v_exp_f32_e32 v161, v161
	v_mul_f32_e32 v166, v166, v186
	v_pk_mul_f32 v[114:115], v[114:115], v[186:187] op_sel_hi:[1,0]
	v_pk_mul_f32 v[116:117], v[116:117], v[186:187] op_sel_hi:[1,0]
	v_pk_mul_f32 v[118:119], v[118:119], v[186:187] op_sel_hi:[1,0]
	v_pk_mul_f32 v[120:121], v[120:121], v[186:187] op_sel_hi:[1,0]
	v_pk_mul_f32 v[122:123], v[122:123], v[186:187] op_sel_hi:[1,0]
	v_pk_mul_f32 v[124:125], v[124:125], v[186:187] op_sel_hi:[1,0]
	v_pk_mul_f32 v[126:127], v[126:127], v[186:187] op_sel_hi:[1,0]
	v_pk_mul_f32 v[128:129], v[128:129], v[186:187] op_sel_hi:[1,0]
	v_pk_mul_f32 v[130:131], v[130:131], v[186:187] op_sel_hi:[1,0]
	v_pk_mul_f32 v[132:133], v[132:133], v[186:187] op_sel_hi:[1,0]
	v_pk_mul_f32 v[134:135], v[134:135], v[186:187] op_sel_hi:[1,0]
	v_pk_mul_f32 v[136:137], v[136:137], v[186:187] op_sel_hi:[1,0]
	v_pk_mul_f32 v[138:139], v[138:139], v[186:187] op_sel_hi:[1,0]
	v_pk_mul_f32 v[140:141], v[140:141], v[186:187] op_sel_hi:[1,0]
	v_pk_mul_f32 v[142:143], v[142:143], v[186:187] op_sel_hi:[1,0]
	v_pk_mul_f32 v[144:145], v[144:145], v[186:187] op_sel_hi:[1,0]
	v_add_f32_e32 v183, v146, v147
	v_add_f32_e32 v184, v148, v149
	v_add_f32_e32 v185, v150, v151
	v_add_f32_e32 v188, v152, v153
	v_add_f32_e32 v183, v183, v154
	v_add_f32_e32 v184, v184, v155
	v_add_f32_e32 v185, v185, v156
	v_add_f32_e32 v188, v188, v157
	v_add_f32_e32 v183, v183, v158
	v_add_f32_e32 v184, v184, v159
	v_add_f32_e32 v185, v185, v160
	v_add_f32_e32 v188, v188, v161
	v_add_f32_e32 v183, v183, v184
	v_add_f32_e32 v185, v185, v188
	v_add_f32_e32 v183, v183, v185
	v_add_f32_e32 v166, v166, v183
	v_cvt_pk_bf16_f32 v146, v146, v147
	v_cvt_pk_bf16_f32 v147, v148, v149
	v_cvt_pk_bf16_f32 v148, v150, v151
	v_cvt_pk_bf16_f32 v149, v152, v153
	v_cvt_pk_bf16_f32 v150, v154, v155
	v_cvt_pk_bf16_f32 v151, v156, v157
	v_cvt_pk_bf16_f32 v152, v158, v159
	v_cvt_pk_bf16_f32 v153, v160, v161
	s_waitcnt vmcnt(14)
	s_nop 1
	v_mfma_f32_32x32x16_bf16 v[114:129], v[78:81], v[146:149], v[114:129]
	v_mfma_f32_32x32x16_bf16 v[130:145], v[86:89], v[146:149], v[130:145]
	v_mfma_f32_32x32x16_bf16 v[114:129], v[82:85], v[150:153], v[114:129]
	v_mfma_f32_32x32x16_bf16 v[130:145], v[90:93], v[150:153], v[130:145]
	s_branch .Lfox_epi
.Lfox_diag2:
	s_add_i32 s18, s16, 1
	s_min_u32 s18, s18, s15
	s_add_i32 s19, s16, 2
	s_min_u32 s19, s19, s15
	s_lshl_b32 s17, s18, 12
	v_add_u32_e32 v183, s17, v162
	global_load_dwordx4 v[78:81], v183, s[6:7]
	global_load_dwordx4 v[82:85], v183, s[6:7] offset:1024
	global_load_dwordx4 v[86:89], v183, s[6:7] offset:2048
	global_load_dwordx4 v[90:93], v183, s[6:7] offset:3072
	s_lshl_b32 s17, s19, 12
	v_add_u32_e32 v183, s17, v162
	global_load_dwordx4 v[22:25], v183, s[4:5]
	global_load_dwordx4 v[26:29], v183, s[4:5] offset:1024
	global_load_dwordx4 v[30:33], v183, s[4:5] offset:2048
	global_load_dwordx4 v[34:37], v183, s[4:5] offset:3072
	s_lshl_b32 s17, s19, 9
	v_add_u32_e32 v183, s17, v190
	s_mov_b64 exec, s[44:45]
	global_load_dwordx4 v[38:41], v183, s[8:9]
	s_mov_b64 exec, -1
	s_waitcnt vmcnt(18)
	v_mfma_f32_32x32x16_bf16 v[146:161], v[42:45], v[94:97], 0
	v_mfma_f32_32x32x16_bf16 v[146:161], v[46:49], v[98:101], v[146:161]
	v_mfma_f32_32x32x16_bf16 v[146:161], v[50:53], v[102:105], v[146:161]
	v_mfma_f32_32x32x16_bf16 v[146:161], v[54:57], v[106:109], v[146:161]
	v_mfma_f32_32x32x16_bf16 v[146:161], v[58:61], v[110:113], v[146:161]
	s_nop 7
	s_nop 4
	v_cmp_le_i32_e64 s[34:35], 0, v170
	v_cmp_le_i32_e64 s[36:37], 1, v170
	v_cmp_le_i32_e64 s[38:39], 2, v170
	v_cmp_le_i32_e64 s[40:41], 3, v170
	v_cmp_le_i32_e32 vcc, 8, v170
	v_cndmask_b32_e64 v146, v193, v146, s[34:35]
	v_cndmask_b32_e64 v147, v193, v147, s[36:37]
	v_cndmask_b32_e64 v148, v193, v148, s[38:39]
	v_cndmask_b32_e64 v149, v193, v149, s[40:41]
	v_cndmask_b32_e64 v150, v193, v150, vcc
	v_cmp_le_i32_e64 s[34:35], 9, v170
	v_cmp_le_i32_e64 s[36:37], 10, v170
	v_cmp_le_i32_e64 s[38:39], 11, v170
	v_cmp_le_i32_e64 s[40:41], 16, v170
	v_cmp_le_i32_e32 vcc, 17, v170
	v_cndmask_b32_e64 v151, v193, v151, s[34:35]
	v_cndmask_b32_e64 v152, v193, v152, s[36:37]
	v_cndmask_b32_e64 v153, v193, v153, s[38:39]
	v_cndmask_b32_e64 v154, v193, v154, s[40:41]
	v_cndmask_b32_e64 v155, v193, v155, vcc
	v_cmp_le_i32_e64 s[34:35], 18, v170
	v_cmp_le_i32_e64 s[36:37], 19, v170
	v_cmp_le_i32_e64 s[38:39], 24, v170
	v_cmp_le_i32_e64 s[40:41], 25, v170
	v_cmp_le_i32_e32 vcc, 26, v170
	v_cndmask_b32_e64 v156, v193, v156, s[34:35]
	v_cndmask_b32_e64 v157, v193, v157, s[36:37]
	v_cndmask_b32_e64 v158, v193, v158, s[38:39]
	v_cndmask_b32_e64 v159, v193, v159, s[40:41]
	v_cndmask_b32_e64 v160, v193, v160, vcc
	v_cmp_le_i32_e64 s[34:35], 27, v170
	s_nop 1
	v_cndmask_b32_e64 v161, v193, v161, s[34:35]
	v_max3_f32 v183, v146, v147, v148
	v_max3_f32 v184, v149, v150, v151
	v_max3_f32 v185, v152, v153, v154
	v_max3_f32 v186, v155, v156, v157
	v_max3_f32 v187, v158, v159, v160
	v_max3_f32 v183, v183, v184, v185
	v_max3_f32 v186, v186, v187, v161
	v_max_f32_e32 v183, v183, v186
	ds_bpermute_b32 v184, v192, v183
	s_waitcnt lgkmcnt(0)
	v_max_f32_e32 v183, v183, v184
	v_fma_f32 v183, v183, s14, v167
	v_max_f32_e32 v184, v165, v183
	v_sub_f32_e32 v186, v165, v184
	v_exp_f32_e32 v186, v186
	v_mov_b32_e32 v165, v184
	v_sub_f32_e32 v168, v167, v184
	v_fma_f32 v146, v146, s14, v168
	v_exp_f32_e32 v146, v146
	v_fma_f32 v147, v147, s14, v168
	v_exp_f32_e32 v147, v147
	v_fma_f32 v148, v148, s14, v168
	v_exp_f32_e32 v148, v148
	v_fma_f32 v149, v149, s14, v168
	v_exp_f32_e32 v149, v149
	v_fma_f32 v150, v150, s14, v168
	v_exp_f32_e32 v150, v150
	v_fma_f32 v151, v151, s14, v168
	v_exp_f32_e32 v151, v151
	v_fma_f32 v152, v152, s14, v168
	v_exp_f32_e32 v152, v152
	v_fma_f32 v153, v153, s14, v168
	v_exp_f32_e32 v153, v153
	v_fma_f32 v154, v154, s14, v168
	v_exp_f32_e32 v154, v154
	v_fma_f32 v155, v155, s14, v168
	v_exp_f32_e32 v155, v155
	v_fma_f32 v156, v156, s14, v168
	v_exp_f32_e32 v156, v156
	v_fma_f32 v157, v157, s14, v168
	v_exp_f32_e32 v157, v157
	v_fma_f32 v158, v158, s14, v168
	v_exp_f32_e32 v158, v158
	v_fma_f32 v159, v159, s14, v168
	v_exp_f32_e32 v159, v159
	v_fma_f32 v160, v160, s14, v168
	v_exp_f32_e32 v160, v160
	v_fma_f32 v161, v161, s14, v168
	v_exp_f32_e32 v161, v161
	v_mul_f32_e32 v166, v166, v186
	v_pk_mul_f32 v[114:115], v[114:115], v[186:187] op_sel_hi:[1,0]
	v_pk_mul_f32 v[116:117], v[116:117], v[186:187] op_sel_hi:[1,0]
	v_pk_mul_f32 v[118:119], v[118:119], v[186:187] op_sel_hi:[1,0]
	v_pk_mul_f32 v[120:121], v[120:121], v[186:187] op_sel_hi:[1,0]
	v_pk_mul_f32 v[122:123], v[122:123], v[186:187] op_sel_hi:[1,0]
	v_pk_mul_f32 v[124:125], v[124:125], v[186:187] op_sel_hi:[1,0]
	v_pk_mul_f32 v[126:127], v[126:127], v[186:187] op_sel_hi:[1,0]
	v_pk_mul_f32 v[128:129], v[128:129], v[186:187] op_sel_hi:[1,0]
	v_pk_mul_f32 v[130:131], v[130:131], v[186:187] op_sel_hi:[1,0]
	v_pk_mul_f32 v[132:133], v[132:133], v[186:187] op_sel_hi:[1,0]
	v_pk_mul_f32 v[134:135], v[134:135], v[186:187] op_sel_hi:[1,0]
	v_pk_mul_f32 v[136:137], v[136:137], v[186:187] op_sel_hi:[1,0]
	v_pk_mul_f32 v[138:139], v[138:139], v[186:187] op_sel_hi:[1,0]
	v_pk_mul_f32 v[140:141], v[140:141], v[186:187] op_sel_hi:[1,0]
	v_pk_mul_f32 v[142:143], v[142:143], v[186:187] op_sel_hi:[1,0]
	v_pk_mul_f32 v[144:145], v[144:145], v[186:187] op_sel_hi:[1,0]
	v_add_f32_e32 v183, v146, v147
	v_add_f32_e32 v184, v148, v149
	v_add_f32_e32 v185, v150, v151
	v_add_f32_e32 v188, v152, v153
	v_add_f32_e32 v183, v183, v154
	v_add_f32_e32 v184, v184, v155
	v_add_f32_e32 v185, v185, v156
	v_add_f32_e32 v188, v188, v157
	v_add_f32_e32 v183, v183, v158
	v_add_f32_e32 v184, v184, v159
	v_add_f32_e32 v185, v185, v160
	v_add_f32_e32 v188, v188, v161
	v_add_f32_e32 v183, v183, v184
	v_add_f32_e32 v185, v185, v188
	v_add_f32_e32 v183, v183, v185
	v_add_f32_e32 v166, v166, v183
	v_cvt_pk_bf16_f32 v146, v146, v147
	v_cvt_pk_bf16_f32 v147, v148, v149
	v_cvt_pk_bf16_f32 v148, v150, v151
	v_cvt_pk_bf16_f32 v149, v152, v153
	v_cvt_pk_bf16_f32 v150, v154, v155
	v_cvt_pk_bf16_f32 v151, v156, v157
	v_cvt_pk_bf16_f32 v152, v158, v159
	v_cvt_pk_bf16_f32 v153, v160, v161
	s_waitcnt vmcnt(14)
	s_nop 1
	v_mfma_f32_32x32x16_bf16 v[114:129], v[62:65], v[146:149], v[114:129]
	v_mfma_f32_32x32x16_bf16 v[130:145], v[70:73], v[146:149], v[130:145]
	v_mfma_f32_32x32x16_bf16 v[114:129], v[66:69], v[150:153], v[114:129]
	v_mfma_f32_32x32x16_bf16 v[130:145], v[74:77], v[150:153], v[130:145]
	s_branch .Lfox_epi
.Lfox_diag3:
	s_add_i32 s18, s16, 1
	s_min_u32 s18, s18, s15
	s_add_i32 s19, s16, 2
	s_min_u32 s19, s19, s15
	s_lshl_b32 s17, s18, 12
	v_add_u32_e32 v183, s17, v162
	global_load_dwordx4 v[62:65], v183, s[6:7]
	global_load_dwordx4 v[66:69], v183, s[6:7] offset:1024
	global_load_dwordx4 v[70:73], v183, s[6:7] offset:2048
	global_load_dwordx4 v[74:77], v183, s[6:7] offset:3072
	s_lshl_b32 s17, s19, 12
	v_add_u32_e32 v183, s17, v162
	global_load_dwordx4 v[42:45], v183, s[4:5]
	global_load_dwordx4 v[46:49], v183, s[4:5] offset:1024
	global_load_dwordx4 v[50:53], v183, s[4:5] offset:2048
	global_load_dwordx4 v[54:57], v183, s[4:5] offset:3072
	s_lshl_b32 s17, s19, 9
	v_add_u32_e32 v183, s17, v190
	s_mov_b64 exec, s[44:45]
	global_load_dwordx4 v[58:61], v183, s[8:9]
	s_mov_b64 exec, -1
	s_waitcnt vmcnt(18)
	v_mfma_f32_32x32x16_bf16 v[146:161], v[2:5], v[94:97], 0
	v_mfma_f32_32x32x16_bf16 v[146:161], v[6:9], v[98:101], v[146:161]
	v_mfma_f32_32x32x16_bf16 v[146:161], v[10:13], v[102:105], v[146:161]
	v_mfma_f32_32x32x16_bf16 v[146:161], v[14:17], v[106:109], v[146:161]
	v_mfma_f32_32x32x16_bf16 v[146:161], v[18:21], v[110:113], v[146:161]
	s_nop 7
	s_nop 4
	v_cmp_le_i32_e64 s[34:35], 0, v170
	v_cmp_le_i32_e64 s[36:37], 1, v170
	v_cmp_le_i32_e64 s[38:39], 2, v170
	v_cmp_le_i32_e64 s[40:41], 3, v170
	v_cmp_le_i32_e32 vcc, 8, v170
	v_cndmask_b32_e64 v146, v193, v146, s[34:35]
	v_cndmask_b32_e64 v147, v193, v147, s[36:37]
	v_cndmask_b32_e64 v148, v193, v148, s[38:39]
	v_cndmask_b32_e64 v149, v193, v149, s[40:41]
	v_cndmask_b32_e64 v150, v193, v150, vcc
	v_cmp_le_i32_e64 s[34:35], 9, v170
	v_cmp_le_i32_e64 s[36:37], 10, v170
	v_cmp_le_i32_e64 s[38:39], 11, v170
	v_cmp_le_i32_e64 s[40:41], 16, v170
	v_cmp_le_i32_e32 vcc, 17, v170
	v_cndmask_b32_e64 v151, v193, v151, s[34:35]
	v_cndmask_b32_e64 v152, v193, v152, s[36:37]
	v_cndmask_b32_e64 v153, v193, v153, s[38:39]
	v_cndmask_b32_e64 v154, v193, v154, s[40:41]
	v_cndmask_b32_e64 v155, v193, v155, vcc
	v_cmp_le_i32_e64 s[34:35], 18, v170
	v_cmp_le_i32_e64 s[36:37], 19, v170
	v_cmp_le_i32_e64 s[38:39], 24, v170
	v_cmp_le_i32_e64 s[40:41], 25, v170
	v_cmp_le_i32_e32 vcc, 26, v170
	v_cndmask_b32_e64 v156, v193, v156, s[34:35]
	v_cndmask_b32_e64 v157, v193, v157, s[36:37]
	v_cndmask_b32_e64 v158, v193, v158, s[38:39]
	v_cndmask_b32_e64 v159, v193, v159, s[40:41]
	v_cndmask_b32_e64 v160, v193, v160, vcc
	v_cmp_le_i32_e64 s[34:35], 27, v170
	s_nop 1
	v_cndmask_b32_e64 v161, v193, v161, s[34:35]
	v_max3_f32 v183, v146, v147, v148
	v_max3_f32 v184, v149, v150, v151
	v_max3_f32 v185, v152, v153, v154
	v_max3_f32 v186, v155, v156, v157
	v_max3_f32 v187, v158, v159, v160
	v_max3_f32 v183, v183, v184, v185
	v_max3_f32 v186, v186, v187, v161
	v_max_f32_e32 v183, v183, v186
	ds_bpermute_b32 v184, v192, v183
	s_waitcnt lgkmcnt(0)
	v_max_f32_e32 v183, v183, v184
	v_fma_f32 v183, v183, s14, v167
	v_max_f32_e32 v184, v165, v183
	v_sub_f32_e32 v186, v165, v184
	v_exp_f32_e32 v186, v186
	v_mov_b32_e32 v165, v184
	v_sub_f32_e32 v168, v167, v184
	v_fma_f32 v146, v146, s14, v168
	v_exp_f32_e32 v146, v146
	v_fma_f32 v147, v147, s14, v168
	v_exp_f32_e32 v147, v147
	v_fma_f32 v148, v148, s14, v168
	v_exp_f32_e32 v148, v148
	v_fma_f32 v149, v149, s14, v168
	v_exp_f32_e32 v149, v149
	v_fma_f32 v150, v150, s14, v168
	v_exp_f32_e32 v150, v150
	v_fma_f32 v151, v151, s14, v168
	v_exp_f32_e32 v151, v151
	v_fma_f32 v152, v152, s14, v168
	v_exp_f32_e32 v152, v152
	v_fma_f32 v153, v153, s14, v168
	v_exp_f32_e32 v153, v153
	v_fma_f32 v154, v154, s14, v168
	v_exp_f32_e32 v154, v154
	v_fma_f32 v155, v155, s14, v168
	v_exp_f32_e32 v155, v155
	v_fma_f32 v156, v156, s14, v168
	v_exp_f32_e32 v156, v156
	v_fma_f32 v157, v157, s14, v168
	v_exp_f32_e32 v157, v157
	v_fma_f32 v158, v158, s14, v168
	v_exp_f32_e32 v158, v158
	v_fma_f32 v159, v159, s14, v168
	v_exp_f32_e32 v159, v159
	v_fma_f32 v160, v160, s14, v168
	v_exp_f32_e32 v160, v160
	v_fma_f32 v161, v161, s14, v168
	v_exp_f32_e32 v161, v161
	v_mul_f32_e32 v166, v166, v186
	v_pk_mul_f32 v[114:115], v[114:115], v[186:187] op_sel_hi:[1,0]
	v_pk_mul_f32 v[116:117], v[116:117], v[186:187] op_sel_hi:[1,0]
	v_pk_mul_f32 v[118:119], v[118:119], v[186:187] op_sel_hi:[1,0]
	v_pk_mul_f32 v[120:121], v[120:121], v[186:187] op_sel_hi:[1,0]
	v_pk_mul_f32 v[122:123], v[122:123], v[186:187] op_sel_hi:[1,0]
	v_pk_mul_f32 v[124:125], v[124:125], v[186:187] op_sel_hi:[1,0]
	v_pk_mul_f32 v[126:127], v[126:127], v[186:187] op_sel_hi:[1,0]
	v_pk_mul_f32 v[128:129], v[128:129], v[186:187] op_sel_hi:[1,0]
	v_pk_mul_f32 v[130:131], v[130:131], v[186:187] op_sel_hi:[1,0]
	v_pk_mul_f32 v[132:133], v[132:133], v[186:187] op_sel_hi:[1,0]
	v_pk_mul_f32 v[134:135], v[134:135], v[186:187] op_sel_hi:[1,0]
	v_pk_mul_f32 v[136:137], v[136:137], v[186:187] op_sel_hi:[1,0]
	v_pk_mul_f32 v[138:139], v[138:139], v[186:187] op_sel_hi:[1,0]
	v_pk_mul_f32 v[140:141], v[140:141], v[186:187] op_sel_hi:[1,0]
	v_pk_mul_f32 v[142:143], v[142:143], v[186:187] op_sel_hi:[1,0]
	v_pk_mul_f32 v[144:145], v[144:145], v[186:187] op_sel_hi:[1,0]
	v_add_f32_e32 v183, v146, v147
	v_add_f32_e32 v184, v148, v149
	v_add_f32_e32 v185, v150, v151
	v_add_f32_e32 v188, v152, v153
	v_add_f32_e32 v183, v183, v154
	v_add_f32_e32 v184, v184, v155
	v_add_f32_e32 v185, v185, v156
	v_add_f32_e32 v188, v188, v157
	v_add_f32_e32 v183, v183, v158
	v_add_f32_e32 v184, v184, v159
	v_add_f32_e32 v185, v185, v160
	v_add_f32_e32 v188, v188, v161
	v_add_f32_e32 v183, v183, v184
	v_add_f32_e32 v185, v185, v188
	v_add_f32_e32 v183, v183, v185
	v_add_f32_e32 v166, v166, v183
	v_cvt_pk_bf16_f32 v146, v146, v147
	v_cvt_pk_bf16_f32 v147, v148, v149
	v_cvt_pk_bf16_f32 v148, v150, v151
	v_cvt_pk_bf16_f32 v149, v152, v153
	v_cvt_pk_bf16_f32 v150, v154, v155
	v_cvt_pk_bf16_f32 v151, v156, v157
	v_cvt_pk_bf16_f32 v152, v158, v159
	v_cvt_pk_bf16_f32 v153, v160, v161
	s_waitcnt vmcnt(14)
	s_nop 1
	v_mfma_f32_32x32x16_bf16 v[114:129], v[78:81], v[146:149], v[114:129]
	v_mfma_f32_32x32x16_bf16 v[130:145], v[86:89], v[146:149], v[130:145]
	v_mfma_f32_32x32x16_bf16 v[114:129], v[82:85], v[150:153], v[114:129]
	v_mfma_f32_32x32x16_bf16 v[130:145], v[90:93], v[150:153], v[130:145]
	s_branch .Lfox_epi
.Lfox_diag4:
	s_add_i32 s18, s16, 1
	s_min_u32 s18, s18, s15
	s_add_i32 s19, s16, 2
	s_min_u32 s19, s19, s15
	s_lshl_b32 s17, s18, 12
	v_add_u32_e32 v183, s17, v162
	global_load_dwordx4 v[78:81], v183, s[6:7]
	global_load_dwordx4 v[82:85], v183, s[6:7] offset:1024
	global_load_dwordx4 v[86:89], v183, s[6:7] offset:2048
	global_load_dwordx4 v[90:93], v183, s[6:7] offset:3072
	s_lshl_b32 s17, s19, 12
	v_add_u32_e32 v183, s17, v162
	global_load_dwordx4 v[2:5], v183, s[4:5]
	global_load_dwordx4 v[6:9], v183, s[4:5] offset:1024
	global_load_dwordx4 v[10:13], v183, s[4:5] offset:2048
	global_load_dwordx4 v[14:17], v183, s[4:5] offset:3072
	s_lshl_b32 s17, s19, 9
	v_add_u32_e32 v183, s17, v190
	s_mov_b64 exec, s[44:45]
	global_load_dwordx4 v[18:21], v183, s[8:9]
	s_mov_b64 exec, -1
	s_waitcnt vmcnt(18)
	v_mfma_f32_32x32x16_bf16 v[146:161], v[22:25], v[94:97], 0
	v_mfma_f32_32x32x16_bf16 v[146:161], v[26:29], v[98:101], v[146:161]
	v_mfma_f32_32x32x16_bf16 v[146:161], v[30:33], v[102:105], v[146:161]
	v_mfma_f32_32x32x16_bf16 v[146:161], v[34:37], v[106:109], v[146:161]
	v_mfma_f32_32x32x16_bf16 v[146:161], v[38:41], v[110:113], v[146:161]
	s_nop 7
	s_nop 4
	v_cmp_le_i32_e64 s[34:35], 0, v170
	v_cmp_le_i32_e64 s[36:37], 1, v170
	v_cmp_le_i32_e64 s[38:39], 2, v170
	v_cmp_le_i32_e64 s[40:41], 3, v170
	v_cmp_le_i32_e32 vcc, 8, v170
	v_cndmask_b32_e64 v146, v193, v146, s[34:35]
	v_cndmask_b32_e64 v147, v193, v147, s[36:37]
	v_cndmask_b32_e64 v148, v193, v148, s[38:39]
	v_cndmask_b32_e64 v149, v193, v149, s[40:41]
	v_cndmask_b32_e64 v150, v193, v150, vcc
	v_cmp_le_i32_e64 s[34:35], 9, v170
	v_cmp_le_i32_e64 s[36:37], 10, v170
	v_cmp_le_i32_e64 s[38:39], 11, v170
	v_cmp_le_i32_e64 s[40:41], 16, v170
	v_cmp_le_i32_e32 vcc, 17, v170
	v_cndmask_b32_e64 v151, v193, v151, s[34:35]
	v_cndmask_b32_e64 v152, v193, v152, s[36:37]
	v_cndmask_b32_e64 v153, v193, v153, s[38:39]
	v_cndmask_b32_e64 v154, v193, v154, s[40:41]
	v_cndmask_b32_e64 v155, v193, v155, vcc
	v_cmp_le_i32_e64 s[34:35], 18, v170
	v_cmp_le_i32_e64 s[36:37], 19, v170
	v_cmp_le_i32_e64 s[38:39], 24, v170
	v_cmp_le_i32_e64 s[40:41], 25, v170
	v_cmp_le_i32_e32 vcc, 26, v170
	v_cndmask_b32_e64 v156, v193, v156, s[34:35]
	v_cndmask_b32_e64 v157, v193, v157, s[36:37]
	v_cndmask_b32_e64 v158, v193, v158, s[38:39]
	v_cndmask_b32_e64 v159, v193, v159, s[40:41]
	v_cndmask_b32_e64 v160, v193, v160, vcc
	v_cmp_le_i32_e64 s[34:35], 27, v170
	s_nop 1
	v_cndmask_b32_e64 v161, v193, v161, s[34:35]
	v_max3_f32 v183, v146, v147, v148
	v_max3_f32 v184, v149, v150, v151
	v_max3_f32 v185, v152, v153, v154
	v_max3_f32 v186, v155, v156, v157
	v_max3_f32 v187, v158, v159, v160
	v_max3_f32 v183, v183, v184, v185
	v_max3_f32 v186, v186, v187, v161
	v_max_f32_e32 v183, v183, v186
	ds_bpermute_b32 v184, v192, v183
	s_waitcnt lgkmcnt(0)
	v_max_f32_e32 v183, v183, v184
	v_fma_f32 v183, v183, s14, v167
	v_max_f32_e32 v184, v165, v183
	v_sub_f32_e32 v186, v165, v184
	v_exp_f32_e32 v186, v186
	v_mov_b32_e32 v165, v184
	v_sub_f32_e32 v168, v167, v184
	v_fma_f32 v146, v146, s14, v168
	v_exp_f32_e32 v146, v146
	v_fma_f32 v147, v147, s14, v168
	v_exp_f32_e32 v147, v147
	v_fma_f32 v148, v148, s14, v168
	v_exp_f32_e32 v148, v148
	v_fma_f32 v149, v149, s14, v168
	v_exp_f32_e32 v149, v149
	v_fma_f32 v150, v150, s14, v168
	v_exp_f32_e32 v150, v150
	v_fma_f32 v151, v151, s14, v168
	v_exp_f32_e32 v151, v151
	v_fma_f32 v152, v152, s14, v168
	v_exp_f32_e32 v152, v152
	v_fma_f32 v153, v153, s14, v168
	v_exp_f32_e32 v153, v153
	v_fma_f32 v154, v154, s14, v168
	v_exp_f32_e32 v154, v154
	v_fma_f32 v155, v155, s14, v168
	v_exp_f32_e32 v155, v155
	v_fma_f32 v156, v156, s14, v168
	v_exp_f32_e32 v156, v156
	v_fma_f32 v157, v157, s14, v168
	v_exp_f32_e32 v157, v157
	v_fma_f32 v158, v158, s14, v168
	v_exp_f32_e32 v158, v158
	v_fma_f32 v159, v159, s14, v168
	v_exp_f32_e32 v159, v159
	v_fma_f32 v160, v160, s14, v168
	v_exp_f32_e32 v160, v160
	v_fma_f32 v161, v161, s14, v168
	v_exp_f32_e32 v161, v161
	v_mul_f32_e32 v166, v166, v186
	v_pk_mul_f32 v[114:115], v[114:115], v[186:187] op_sel_hi:[1,0]
	v_pk_mul_f32 v[116:117], v[116:117], v[186:187] op_sel_hi:[1,0]
	v_pk_mul_f32 v[118:119], v[118:119], v[186:187] op_sel_hi:[1,0]
	v_pk_mul_f32 v[120:121], v[120:121], v[186:187] op_sel_hi:[1,0]
	v_pk_mul_f32 v[122:123], v[122:123], v[186:187] op_sel_hi:[1,0]
	v_pk_mul_f32 v[124:125], v[124:125], v[186:187] op_sel_hi:[1,0]
	v_pk_mul_f32 v[126:127], v[126:127], v[186:187] op_sel_hi:[1,0]
	v_pk_mul_f32 v[128:129], v[128:129], v[186:187] op_sel_hi:[1,0]
	v_pk_mul_f32 v[130:131], v[130:131], v[186:187] op_sel_hi:[1,0]
	v_pk_mul_f32 v[132:133], v[132:133], v[186:187] op_sel_hi:[1,0]
	v_pk_mul_f32 v[134:135], v[134:135], v[186:187] op_sel_hi:[1,0]
	v_pk_mul_f32 v[136:137], v[136:137], v[186:187] op_sel_hi:[1,0]
	v_pk_mul_f32 v[138:139], v[138:139], v[186:187] op_sel_hi:[1,0]
	v_pk_mul_f32 v[140:141], v[140:141], v[186:187] op_sel_hi:[1,0]
	v_pk_mul_f32 v[142:143], v[142:143], v[186:187] op_sel_hi:[1,0]
	v_pk_mul_f32 v[144:145], v[144:145], v[186:187] op_sel_hi:[1,0]
	v_add_f32_e32 v183, v146, v147
	v_add_f32_e32 v184, v148, v149
	v_add_f32_e32 v185, v150, v151
	v_add_f32_e32 v188, v152, v153
	v_add_f32_e32 v183, v183, v154
	v_add_f32_e32 v184, v184, v155
	v_add_f32_e32 v185, v185, v156
	v_add_f32_e32 v188, v188, v157
	v_add_f32_e32 v183, v183, v158
	v_add_f32_e32 v184, v184, v159
	v_add_f32_e32 v185, v185, v160
	v_add_f32_e32 v188, v188, v161
	v_add_f32_e32 v183, v183, v184
	v_add_f32_e32 v185, v185, v188
	v_add_f32_e32 v183, v183, v185
	v_add_f32_e32 v166, v166, v183
	v_cvt_pk_bf16_f32 v146, v146, v147
	v_cvt_pk_bf16_f32 v147, v148, v149
	v_cvt_pk_bf16_f32 v148, v150, v151
	v_cvt_pk_bf16_f32 v149, v152, v153
	v_cvt_pk_bf16_f32 v150, v154, v155
	v_cvt_pk_bf16_f32 v151, v156, v157
	v_cvt_pk_bf16_f32 v152, v158, v159
	v_cvt_pk_bf16_f32 v153, v160, v161
	s_waitcnt vmcnt(14)
	s_nop 1
	v_mfma_f32_32x32x16_bf16 v[114:129], v[62:65], v[146:149], v[114:129]
	v_mfma_f32_32x32x16_bf16 v[130:145], v[70:73], v[146:149], v[130:145]
	v_mfma_f32_32x32x16_bf16 v[114:129], v[66:69], v[150:153], v[114:129]
	v_mfma_f32_32x32x16_bf16 v[130:145], v[74:77], v[150:153], v[130:145]
	s_branch .Lfox_epi
.Lfox_diag5:
	s_add_i32 s18, s16, 1
	s_min_u32 s18, s18, s15
	s_add_i32 s19, s16, 2
	s_min_u32 s19, s19, s15
	s_lshl_b32 s17, s18, 12
	v_add_u32_e32 v183, s17, v162
	global_load_dwordx4 v[62:65], v183, s[6:7]
	global_load_dwordx4 v[66:69], v183, s[6:7] offset:1024
	global_load_dwordx4 v[70:73], v183, s[6:7] offset:2048
	global_load_dwordx4 v[74:77], v183, s[6:7] offset:3072
	s_lshl_b32 s17, s19, 12
	v_add_u32_e32 v183, s17, v162
	global_load_dwordx4 v[22:25], v183, s[4:5]
	global_load_dwordx4 v[26:29], v183, s[4:5] offset:1024
	global_load_dwordx4 v[30:33], v183, s[4:5] offset:2048
	global_load_dwordx4 v[34:37], v183, s[4:5] offset:3072
	s_lshl_b32 s17, s19, 9
	v_add_u32_e32 v183, s17, v190
	s_mov_b64 exec, s[44:45]
	global_load_dwordx4 v[38:41], v183, s[8:9]
	s_mov_b64 exec, -1
	s_waitcnt vmcnt(18)
	v_mfma_f32_32x32x16_bf16 v[146:161], v[42:45], v[94:97], 0
	v_mfma_f32_32x32x16_bf16 v[146:161], v[46:49], v[98:101], v[146:161]
	v_mfma_f32_32x32x16_bf16 v[146:161], v[50:53], v[102:105], v[146:161]
	v_mfma_f32_32x32x16_bf16 v[146:161], v[54:57], v[106:109], v[146:161]
	v_mfma_f32_32x32x16_bf16 v[146:161], v[58:61], v[110:113], v[146:161]
	s_nop 7
	s_nop 4
	v_cmp_le_i32_e64 s[34:35], 0, v170
	v_cmp_le_i32_e64 s[36:37], 1, v170
	v_cmp_le_i32_e64 s[38:39], 2, v170
	v_cmp_le_i32_e64 s[40:41], 3, v170
	v_cmp_le_i32_e32 vcc, 8, v170
	v_cndmask_b32_e64 v146, v193, v146, s[34:35]
	v_cndmask_b32_e64 v147, v193, v147, s[36:37]
	v_cndmask_b32_e64 v148, v193, v148, s[38:39]
	v_cndmask_b32_e64 v149, v193, v149, s[40:41]
	v_cndmask_b32_e64 v150, v193, v150, vcc
	v_cmp_le_i32_e64 s[34:35], 9, v170
	v_cmp_le_i32_e64 s[36:37], 10, v170
	v_cmp_le_i32_e64 s[38:39], 11, v170
	v_cmp_le_i32_e64 s[40:41], 16, v170
	v_cmp_le_i32_e32 vcc, 17, v170
	v_cndmask_b32_e64 v151, v193, v151, s[34:35]
	v_cndmask_b32_e64 v152, v193, v152, s[36:37]
	v_cndmask_b32_e64 v153, v193, v153, s[38:39]
	v_cndmask_b32_e64 v154, v193, v154, s[40:41]
	v_cndmask_b32_e64 v155, v193, v155, vcc
	v_cmp_le_i32_e64 s[34:35], 18, v170
	v_cmp_le_i32_e64 s[36:37], 19, v170
	v_cmp_le_i32_e64 s[38:39], 24, v170
	v_cmp_le_i32_e64 s[40:41], 25, v170
	v_cmp_le_i32_e32 vcc, 26, v170
	v_cndmask_b32_e64 v156, v193, v156, s[34:35]
	v_cndmask_b32_e64 v157, v193, v157, s[36:37]
	v_cndmask_b32_e64 v158, v193, v158, s[38:39]
	v_cndmask_b32_e64 v159, v193, v159, s[40:41]
	v_cndmask_b32_e64 v160, v193, v160, vcc
	v_cmp_le_i32_e64 s[34:35], 27, v170
	s_nop 1
	v_cndmask_b32_e64 v161, v193, v161, s[34:35]
	v_max3_f32 v183, v146, v147, v148
	v_max3_f32 v184, v149, v150, v151
	v_max3_f32 v185, v152, v153, v154
	v_max3_f32 v186, v155, v156, v157
	v_max3_f32 v187, v158, v159, v160
	v_max3_f32 v183, v183, v184, v185
	v_max3_f32 v186, v186, v187, v161
	v_max_f32_e32 v183, v183, v186
	ds_bpermute_b32 v184, v192, v183
	s_waitcnt lgkmcnt(0)
	v_max_f32_e32 v183, v183, v184
	v_fma_f32 v183, v183, s14, v167
	v_max_f32_e32 v184, v165, v183
	v_sub_f32_e32 v186, v165, v184
	v_exp_f32_e32 v186, v186
	v_mov_b32_e32 v165, v184
	v_sub_f32_e32 v168, v167, v184
	v_fma_f32 v146, v146, s14, v168
	v_exp_f32_e32 v146, v146
	v_fma_f32 v147, v147, s14, v168
	v_exp_f32_e32 v147, v147
	v_fma_f32 v148, v148, s14, v168
	v_exp_f32_e32 v148, v148
	v_fma_f32 v149, v149, s14, v168
	v_exp_f32_e32 v149, v149
	v_fma_f32 v150, v150, s14, v168
	v_exp_f32_e32 v150, v150
	v_fma_f32 v151, v151, s14, v168
	v_exp_f32_e32 v151, v151
	v_fma_f32 v152, v152, s14, v168
	v_exp_f32_e32 v152, v152
	v_fma_f32 v153, v153, s14, v168
	v_exp_f32_e32 v153, v153
	v_fma_f32 v154, v154, s14, v168
	v_exp_f32_e32 v154, v154
	v_fma_f32 v155, v155, s14, v168
	v_exp_f32_e32 v155, v155
	v_fma_f32 v156, v156, s14, v168
	v_exp_f32_e32 v156, v156
	v_fma_f32 v157, v157, s14, v168
	v_exp_f32_e32 v157, v157
	v_fma_f32 v158, v158, s14, v168
	v_exp_f32_e32 v158, v158
	v_fma_f32 v159, v159, s14, v168
	v_exp_f32_e32 v159, v159
	v_fma_f32 v160, v160, s14, v168
	v_exp_f32_e32 v160, v160
	v_fma_f32 v161, v161, s14, v168
	v_exp_f32_e32 v161, v161
	v_mul_f32_e32 v166, v166, v186
	v_pk_mul_f32 v[114:115], v[114:115], v[186:187] op_sel_hi:[1,0]
	v_pk_mul_f32 v[116:117], v[116:117], v[186:187] op_sel_hi:[1,0]
	v_pk_mul_f32 v[118:119], v[118:119], v[186:187] op_sel_hi:[1,0]
	v_pk_mul_f32 v[120:121], v[120:121], v[186:187] op_sel_hi:[1,0]
	v_pk_mul_f32 v[122:123], v[122:123], v[186:187] op_sel_hi:[1,0]
	v_pk_mul_f32 v[124:125], v[124:125], v[186:187] op_sel_hi:[1,0]
	v_pk_mul_f32 v[126:127], v[126:127], v[186:187] op_sel_hi:[1,0]
	v_pk_mul_f32 v[128:129], v[128:129], v[186:187] op_sel_hi:[1,0]
	v_pk_mul_f32 v[130:131], v[130:131], v[186:187] op_sel_hi:[1,0]
	v_pk_mul_f32 v[132:133], v[132:133], v[186:187] op_sel_hi:[1,0]
	v_pk_mul_f32 v[134:135], v[134:135], v[186:187] op_sel_hi:[1,0]
	v_pk_mul_f32 v[136:137], v[136:137], v[186:187] op_sel_hi:[1,0]
	v_pk_mul_f32 v[138:139], v[138:139], v[186:187] op_sel_hi:[1,0]
	v_pk_mul_f32 v[140:141], v[140:141], v[186:187] op_sel_hi:[1,0]
	v_pk_mul_f32 v[142:143], v[142:143], v[186:187] op_sel_hi:[1,0]
	v_pk_mul_f32 v[144:145], v[144:145], v[186:187] op_sel_hi:[1,0]
	v_add_f32_e32 v183, v146, v147
	v_add_f32_e32 v184, v148, v149
	v_add_f32_e32 v185, v150, v151
	v_add_f32_e32 v188, v152, v153
	v_add_f32_e32 v183, v183, v154
	v_add_f32_e32 v184, v184, v155
	v_add_f32_e32 v185, v185, v156
	v_add_f32_e32 v188, v188, v157
	v_add_f32_e32 v183, v183, v158
	v_add_f32_e32 v184, v184, v159
	v_add_f32_e32 v185, v185, v160
	v_add_f32_e32 v188, v188, v161
	v_add_f32_e32 v183, v183, v184
	v_add_f32_e32 v185, v185, v188
	v_add_f32_e32 v183, v183, v185
	v_add_f32_e32 v166, v166, v183
	v_cvt_pk_bf16_f32 v146, v146, v147
	v_cvt_pk_bf16_f32 v147, v148, v149
	v_cvt_pk_bf16_f32 v148, v150, v151
	v_cvt_pk_bf16_f32 v149, v152, v153
	v_cvt_pk_bf16_f32 v150, v154, v155
	v_cvt_pk_bf16_f32 v151, v156, v157
	v_cvt_pk_bf16_f32 v152, v158, v159
	v_cvt_pk_bf16_f32 v153, v160, v161
	s_waitcnt vmcnt(14)
	s_nop 1
	v_mfma_f32_32x32x16_bf16 v[114:129], v[78:81], v[146:149], v[114:129]
	v_mfma_f32_32x32x16_bf16 v[130:145], v[86:89], v[146:149], v[130:145]
	v_mfma_f32_32x32x16_bf16 v[114:129], v[82:85], v[150:153], v[114:129]
	v_mfma_f32_32x32x16_bf16 v[130:145], v[90:93], v[150:153], v[130:145]
	s_branch .Lfox_epi
.Lfox_epi:
	s_nop 7
	s_nop 7
	ds_bpermute_b32 v184, v192, v166
	s_waitcnt lgkmcnt(0)
	v_add_f32_e32 v166, v166, v184
	v_rcp_f32_e32 v186, v166
	s_nop 0
	v_fma_f32 v184, -v166, v186, 1.0
	v_fma_f32 v186, v186, v184, v186
	v_pk_mul_f32 v[114:115], v[114:115], v[186:187] op_sel_hi:[1,0]
	v_pk_mul_f32 v[116:117], v[116:117], v[186:187] op_sel_hi:[1,0]
	v_pk_mul_f32 v[118:119], v[118:119], v[186:187] op_sel_hi:[1,0]
	v_pk_mul_f32 v[120:121], v[120:121], v[186:187] op_sel_hi:[1,0]
	v_pk_mul_f32 v[122:123], v[122:123], v[186:187] op_sel_hi:[1,0]
	v_pk_mul_f32 v[124:125], v[124:125], v[186:187] op_sel_hi:[1,0]
	v_pk_mul_f32 v[126:127], v[126:127], v[186:187] op_sel_hi:[1,0]
	v_pk_mul_f32 v[128:129], v[128:129], v[186:187] op_sel_hi:[1,0]
	v_pk_mul_f32 v[130:131], v[130:131], v[186:187] op_sel_hi:[1,0]
	v_pk_mul_f32 v[132:133], v[132:133], v[186:187] op_sel_hi:[1,0]
	v_pk_mul_f32 v[134:135], v[134:135], v[186:187] op_sel_hi:[1,0]
	v_pk_mul_f32 v[136:137], v[136:137], v[186:187] op_sel_hi:[1,0]
	v_pk_mul_f32 v[138:139], v[138:139], v[186:187] op_sel_hi:[1,0]
	v_pk_mul_f32 v[140:141], v[140:141], v[186:187] op_sel_hi:[1,0]
	v_pk_mul_f32 v[142:143], v[142:143], v[186:187] op_sel_hi:[1,0]
	v_pk_mul_f32 v[144:145], v[144:145], v[186:187] op_sel_hi:[1,0]
	v_cvt_pk_bf16_f32 v114, v114, v115
	v_cvt_pk_bf16_f32 v115, v116, v117
	global_store_dwordx2 v191, v[114:115], s[12:13]
	v_cvt_pk_bf16_f32 v118, v118, v119
	v_cvt_pk_bf16_f32 v119, v120, v121
	global_store_dwordx2 v191, v[118:119], s[12:13] offset:16
	v_cvt_pk_bf16_f32 v122, v122, v123
	v_cvt_pk_bf16_f32 v123, v124, v125
	global_store_dwordx2 v191, v[122:123], s[12:13] offset:32
	v_cvt_pk_bf16_f32 v126, v126, v127
	v_cvt_pk_bf16_f32 v127, v128, v129
	global_store_dwordx2 v191, v[126:127], s[12:13] offset:48
	v_cvt_pk_bf16_f32 v130, v130, v131
	v_cvt_pk_bf16_f32 v131, v132, v133
	global_store_dwordx2 v191, v[130:131], s[12:13] offset:64
	v_cvt_pk_bf16_f32 v134, v134, v135
	v_cvt_pk_bf16_f32 v135, v136, v137
	global_store_dwordx2 v191, v[134:135], s[12:13] offset:80
	v_cvt_pk_bf16_f32 v138, v138, v139
	v_cvt_pk_bf16_f32 v139, v140, v141
	global_store_dwordx2 v191, v[138:139], s[12:13] offset:96
	v_cvt_pk_bf16_f32 v142, v142, v143
	v_cvt_pk_bf16_f32 v143, v144, v145
	global_store_dwordx2 v191, v[142:143], s[12:13] offset:112
	s_waitcnt vmcnt(0)
	s_add_i32 s28, s28, 1
	s_mov_b32 s15, s24
	s_cmp_lt_u32 s28, 2
	s_cbranch_scc1 .Lfox_item
	s_add_i32 s22, s22, s68
	s_cmpk_lt_i32 s22, 0x800
	s_cbranch_scc1 .Lfox_outer
	v_lshlrev_b32_e32 v2, 2, v220
	v_add_u32_e32 v3, 0x10000, v2
	ds_read_b32 v162, v2 offset:0
	ds_read_b32 v163, v2 offset:2048
	ds_read_b32 v164, v2 offset:4096
	ds_read_b32 v165, v2 offset:6144
	ds_read_b32 v166, v2 offset:8192
	ds_read_b32 v167, v2 offset:10240
	ds_read_b32 v168, v2 offset:12288
	ds_read_b32 v169, v2 offset:14336
	ds_read_b32 v170, v2 offset:16384
	ds_read_b32 v183, v2 offset:18432
	ds_read_b32 v184, v2 offset:20480
	ds_read_b32 v185, v2 offset:22528
	ds_read_b32 v186, v2 offset:24576
	ds_read_b32 v187, v2 offset:26624
	ds_read_b32 v188, v2 offset:28672
	ds_read_b32 v189, v2 offset:30720
	ds_read_b32 v190, v2 offset:32768
	ds_read_b32 v191, v2 offset:34816
	ds_read_b32 v192, v2 offset:36864
	ds_read_b32 v193, v2 offset:38912
	ds_read_b32 v194, v2 offset:40960
	ds_read_b32 v195, v2 offset:43008
	ds_read_b32 v196, v2 offset:45056
	ds_read_b32 v197, v2 offset:47104
	ds_read_b32 v198, v2 offset:49152
	ds_read_b32 v199, v2 offset:51200
	ds_read_b32 v200, v2 offset:53248
	ds_read_b32 v201, v2 offset:55296
	ds_read_b32 v202, v2 offset:57344
	ds_read_b32 v203, v2 offset:59392
	ds_read_b32 v204, v2 offset:61440
	ds_read_b32 v205, v2 offset:63488
	ds_read_b32 v206, v3 offset:0
	ds_read_b32 v207, v3 offset:2048
	ds_read_b32 v208, v3 offset:4096
	ds_read_b32 v209, v3 offset:6144
	ds_read_b32 v210, v3 offset:8192
	ds_read_b32 v211, v3 offset:10240
	ds_read_b32 v212, v3 offset:12288
	ds_read_b32 v213, v3 offset:14336
	ds_read_b32 v214, v3 offset:16384
	ds_read_b32 v215, v3 offset:18432
	ds_read_b32 v216, v3 offset:20480
	ds_read_b32 v146, v3 offset:22528
	ds_read_b32 v147, v3 offset:24576
	ds_read_b32 v148, v3 offset:26624
	ds_read_b32 v149, v3 offset:28672
	ds_read_b32 v150, v3 offset:30720
	ds_read_b32 v151, v3 offset:32768
	ds_read_b32 v152, v3 offset:34816
	ds_read_b32 v153, v3 offset:36864
	ds_read_b32 v154, v3 offset:38912
	ds_read_b32 v155, v3 offset:40960
	ds_read_b32 v156, v3 offset:43008
	ds_read_b32 v157, v3 offset:45056
	ds_read_b32 v158, v3 offset:47104
	ds_read_b32 v159, v3 offset:49152
	ds_read_b32 v160, v3 offset:51200
	ds_read_b32 v161, v3 offset:53248
	v_lshrrev_b32_e32 v2, 6, v220
	v_lshlrev_b32_e32 v2, 8, v2
	v_add_u32_e32 v2, 0x1d800, v2
	ds_read_b32 v4, v2 offset:0
	ds_read_b32 v5, v2 offset:4
	ds_read_b32 v6, v2 offset:8
	ds_read_b32 v7, v2 offset:12
	ds_read_b32 v8, v2 offset:16
	ds_read_b32 v9, v2 offset:20
	ds_read_b32 v10, v2 offset:24
	ds_read_b32 v11, v2 offset:28
	ds_read_b32 v12, v2 offset:32
	ds_read_b32 v13, v2 offset:36
	ds_read_b32 v14, v2 offset:40
	ds_read_b32 v15, v2 offset:44
	ds_read_b32 v16, v2 offset:48
	ds_read_b32 v17, v2 offset:52
	ds_read_b32 v18, v2 offset:56
	ds_read_b32 v19, v2 offset:60
	ds_read_b32 v20, v2 offset:64
	ds_read_b32 v21, v2 offset:68
	ds_read_b32 v22, v2 offset:72
	ds_read_b32 v23, v2 offset:76
	ds_read_b32 v24, v2 offset:80
	ds_read_b32 v25, v2 offset:84
	ds_read_b32 v26, v2 offset:88
	ds_read_b32 v27, v2 offset:92
	ds_read_b32 v28, v2 offset:96
	ds_read_b32 v29, v2 offset:100
	ds_read_b32 v30, v2 offset:104
	ds_read_b32 v31, v2 offset:108
	ds_read_b32 v32, v2 offset:112
	ds_read_b32 v33, v2 offset:116
	ds_read_b32 v34, v2 offset:120
	ds_read_b32 v35, v2 offset:124
	ds_read_b32 v36, v2 offset:128
	ds_read_b32 v37, v2 offset:132
	ds_read_b32 v38, v2 offset:136
	ds_read_b32 v39, v2 offset:140
	ds_read_b32 v40, v2 offset:144
	ds_read_b32 v41, v2 offset:148
	ds_read_b32 v42, v2 offset:152
	ds_read_b32 v43, v2 offset:156
	ds_read_b32 v44, v2 offset:160
	ds_read_b32 v45, v2 offset:164
	s_waitcnt lgkmcnt(0)
	v_readfirstlane_b32 s2, v4
	v_readfirstlane_b32 s3, v5
	v_readfirstlane_b32 s4, v6
	v_readfirstlane_b32 s5, v7
	v_readfirstlane_b32 s6, v8
	v_readfirstlane_b32 s7, v9
	v_readfirstlane_b32 s8, v10
	v_readfirstlane_b32 s9, v11
	v_readfirstlane_b32 s10, v12
	v_readfirstlane_b32 s11, v13
	v_readfirstlane_b32 s12, v14
	v_readfirstlane_b32 s13, v15
	v_readfirstlane_b32 s14, v16
	v_readfirstlane_b32 s15, v17
	v_readfirstlane_b32 s16, v18
	v_readfirstlane_b32 s17, v19
	v_readfirstlane_b32 s18, v20
	v_readfirstlane_b32 s19, v21
	v_readfirstlane_b32 s20, v22
	v_readfirstlane_b32 s21, v23
	v_readfirstlane_b32 s22, v24
	v_readfirstlane_b32 s23, v25
	v_readfirstlane_b32 s24, v26
	v_readfirstlane_b32 s25, v27
	v_readfirstlane_b32 s26, v28
	v_readfirstlane_b32 s27, v29
	v_readfirstlane_b32 s28, v30
	v_readfirstlane_b32 s29, v31
	v_readfirstlane_b32 s30, v32
	v_readfirstlane_b32 s31, v33
	v_readfirstlane_b32 s34, v34
	v_readfirstlane_b32 s35, v35
	v_readfirstlane_b32 s36, v36
	v_readfirstlane_b32 s37, v37
	v_readfirstlane_b32 s38, v38
	v_readfirstlane_b32 s39, v39
	v_readfirstlane_b32 s40, v40
	v_readfirstlane_b32 s41, v41
	v_readfirstlane_b32 s42, v42
	v_readfirstlane_b32 s43, v43
	v_readfirstlane_b32 s44, v44
	v_readfirstlane_b32 s45, v45
	s_barrier
	s_branch .LBB0_715
